# K-loops: one static s_setprio 1 for the trailing half-workgroup (no per-segment toggling)
# speedup vs baseline: 1.0054x; 1.0003x over previous
; #define PG8_STAGE(bufoff, gbase, voff) do { _Pragma("unroll") for (int _i = 0; _i < 2; ++_i) \
;         __builtin_amdgcn_global_load_lds((const unsigned*)((const char*)(gbase) + (voff)[_i]), (PG8_LAS unsigned*)(lds + (bufoff) + ldsw + _i * 8192), 16, 0, 0); } while (0)
; #define PG8_LDA(dst, b, h) do { _Pragma("unroll") for (int m = 0; m < 4; ++m) _Pragma("unroll") for (int k = 0; k < 2; ++k) dst[m][k] = *(const PG8_LAS bf16x8*)(lds + PG8_SA(b, h) + aoff + m * 2048 + k * 1024); } while (0)
; #define PG8_LDB(dst, b, h) do { _Pragma("unroll") for (int n = 0; n < 2; ++n) _Pragma("unroll") for (int k = 0; k < 2; ++k) dst[n][k] = *(const PG8_LAS bf16x8*)(lds + PG8_SB(b, h) + boff + n * 2048 + k * 1024); } while (0)
; #define PG8_SCHED __builtin_amdgcn_sched_barrier(0)
; template <class Epi, class Sched, bool ALIGN_EPI = false, bool SP2 = false>
; __device__ __forceinline__ void gemm_phase(PG8_LAS unsigned char* lds, const Gemm g, const Sched& S, const Epi& E) {
;     ...
;         const bool has_next = S.next(ui + 1, nxt);
;         const char* nA = has_next ? (const char*)g.A + (size_t)nxt.pm * tstep : cA; const char* nB = has_next ? (const char*)g.Bt + (size_t)nxt.pn * tstep : cB;
;         for (int t = 0; t < nt; t += 2) {
;             const bool last = (t == nt - 2);
;             const char* a1 = cA + (size_t)(t + 1) * kstep;
;             const char* a2 = last ? nA : cA + (size_t)(t + 2) * kstep; const char* b2 = last ? nB : cB + (size_t)(t + 2) * kstep;
;             const char* a3 = a2 + kstep; const char* b3 = b2 + kstep;
;             if (last && has_next) S.a_ready(nxt);
;             if constexpr (SP2) {
;             PG8_LDB(B0, 0, 0); PG8_LDB(B1, 0, 1); PG8_SCHED; PG8_LDA(At, 0, 0); PG8_STAGE(PG8_SA(1, 1), a1 + hstep, voffA);
.LBB0_109:
	s_ashr_i32 s75, s74, 31
	s_lshl_b64 s[60:61], s[74:75], 19
	s_add_u32 s76, s40, s60
	s_addc_u32 s77, s41, s61
	s_and_b64 s[60:61], s[4:5], exec
	s_cselect_b32 s1, s77, s7
	s_cselect_b32 s33, s76, s6
	s_ashr_i32 s73, s72, 31
	s_lshl_b64 s[60:61], s[72:73], 19
	s_add_u32 s78, s20, s60
	s_addc_u32 s79, s21, s61
	s_and_b64 s[60:61], s[4:5], exec
	s_cselect_b32 s60, s79, s9
	s_cselect_b32 s61, s78, s8
	s_add_u32 s6, s6, 0x40080
	s_addc_u32 s7, s7, 0
	s_add_u32 s73, s8, 0x100
	s_addc_u32 s75, s9, 0
	s_mov_b32 s84, -2
	s_bitcmp1_b32 s68, 0
	s_cbranch_scc1 .Lnp_110
	s_setprio 1
.Lnp_110:
	ds_read_b128 v[146:149], v160
	ds_read_b128 v[150:153], v160 offset:1024
	ds_read_b128 v[154:157], v160 offset:2048
	ds_read_b128 v[166:169], v160 offset:3072
	ds_read_b128 v[170:173], v161
	ds_read_b128 v[174:177], v161 offset:1024
	ds_read_b128 v[178:181], v161 offset:2048
	ds_read_b128 v[182:185], v161 offset:3072
	s_add_u32 s8, s6, 0xfffc0080
	s_addc_u32 s9, s7, -1
	s_cmp_eq_u32 s84, 12
	s_cselect_b32 s83, s1, s9
	s_cselect_b32 s82, s33, s8
	s_cselect_b32 s9, s60, s75
	s_cselect_b32 s8, s61, s73
	v_lshl_add_u64 v[220:221], s[6:7], 0, v[138:139]
	s_add_i32 m0, s81, 0xc000
	ds_read_b128 v[186:189], v162
	ds_read_b128 v[190:193], v162 offset:1024
	ds_read_b128 v[194:197], v162 offset:2048
	ds_read_b128 v[198:201], v162 offset:3072
	ds_read_b128 v[202:205], v162 offset:4096
	ds_read_b128 v[208:211], v162 offset:5120
	ds_read_b128 v[212:215], v162 offset:6144
	ds_read_b128 v[216:219], v162 offset:7168
	global_load_lds_dwordx4 v[220:221], off
	v_lshl_add_u64 v[220:221], s[6:7], 0, v[140:141]
	s_add_i32 m0, s81, 0xe000
	s_nop 0
	global_load_lds_dwordx4 v[220:221], off
	s_waitcnt vmcnt(24)
	s_cmp_gt_u32 s91, 1
	s_cbranch_scc1 .Lpw_110_0
	s_waitcnt vmcnt(8)

; #define PG8_STAGE(bufoff, gbase, voff) do { _Pragma("unroll") for (int _i = 0; _i < 2; ++_i) \
;         __builtin_amdgcn_global_load_lds((const unsigned*)((const char*)(gbase) + (voff)[_i]), (PG8_LAS unsigned*)(lds + (bufoff) + ldsw + _i * 8192), 16, 0, 0); } while (0)
; #define PG8_LDA(dst, b, h) do { _Pragma("unroll") for (int m = 0; m < 4; ++m) _Pragma("unroll") for (int k = 0; k < 2; ++k) dst[m][k] = *(const PG8_LAS bf16x8*)(lds + PG8_SA(b, h) + aoff + m * 2048 + k * 1024); } while (0)
; #define PG8_LDB(dst, b, h) do { _Pragma("unroll") for (int n = 0; n < 2; ++n) _Pragma("unroll") for (int k = 0; k < 2; ++k) dst[n][k] = *(const PG8_LAS bf16x8*)(lds + PG8_SB(b, h) + boff + n * 2048 + k * 1024); } while (0)
; #define PG8_MMA(ai, bj, At, Bt) do { __builtin_amdgcn_s_setprio(1); _Pragma("unroll") for (int m = 0; m < 4; ++m) _Pragma("unroll") for (int n = 0; n < 2; ++n) _Pragma("unroll") for (int k = 0; k < 2; ++k) \
;         acc[ai][bj][m][n] = __builtin_amdgcn_mfma_f32_16x16x32_bf16(Bt[n][k], At[m][k], acc[ai][bj][m][n], 0, 0, 0); __builtin_amdgcn_s_setprio(0); } while (0)
; #define PG8_WAIT_V(n) asm volatile("s_waitcnt vmcnt(" #n ")" ::: "memory")
; #define PG8_WAIT_L(n) asm volatile("s_waitcnt lgkmcnt(" #n ")" ::: "memory")
; #define PG8_BAR __builtin_amdgcn_s_barrier()
; #define PG8_SCHED __builtin_amdgcn_sched_barrier(0)
; template <class Epi, class Sched, bool ALIGN_EPI = false, bool SP2 = false>
; __device__ __forceinline__ void gemm_phase(PG8_LAS unsigned char* lds, const Gemm g, const Sched& S, const Epi& E) {
;     ...
;             PG8_LDB(B0, 0, 0); PG8_LDB(B1, 0, 1); PG8_SCHED; PG8_LDA(At, 0, 0); PG8_STAGE(PG8_SA(1, 1), a1 + hstep, voffA);
;             PG8_WAIT_V(8); PG8_WAIT_L(0); PG8_BAR; PG8_MMA(0, 0, At, B0); PG8_MMA(0, 1, At, B1); PG8_BAR; PG8_SCHED;
;             PG8_LDA(At, 0, 1); PG8_STAGE(PG8_SB(0, 0), b2, voffB); PG8_STAGE(PG8_SB(0, 1), b2 + hstep, voffB); PG8_STAGE(PG8_SA(0, 0), a2, voffA);
;             PG8_WAIT_V(8); PG8_WAIT_L(0); PG8_BAR; PG8_MMA(1, 0, At, B0); PG8_MMA(1, 1, At, B1); PG8_BAR; PG8_SCHED;
.LBB0_110:
	ds_read_b128 v[146:149], v160
	ds_read_b128 v[150:153], v160 offset:1024
	ds_read_b128 v[154:157], v160 offset:2048
	ds_read_b128 v[166:169], v160 offset:3072
	ds_read_b128 v[170:173], v161
	ds_read_b128 v[174:177], v161 offset:1024
	ds_read_b128 v[178:181], v161 offset:2048
	ds_read_b128 v[182:185], v161 offset:3072
	s_add_u32 s8, s6, 0xfffc0080
	s_addc_u32 s9, s7, -1
	s_cmp_eq_u32 s84, 12
	s_cselect_b32 s83, s1, s9
	s_cselect_b32 s82, s33, s8
	s_cselect_b32 s9, s60, s75
	s_cselect_b32 s8, s61, s73
	v_lshl_add_u64 v[220:221], s[6:7], 0, v[138:139]
	s_add_i32 m0, s81, 0xc000
	ds_read_b128 v[186:189], v162
	ds_read_b128 v[190:193], v162 offset:1024
	ds_read_b128 v[194:197], v162 offset:2048
	ds_read_b128 v[198:201], v162 offset:3072
	ds_read_b128 v[202:205], v162 offset:4096
	ds_read_b128 v[208:211], v162 offset:5120
	ds_read_b128 v[212:215], v162 offset:6144
	ds_read_b128 v[216:219], v162 offset:7168
	global_load_lds_dwordx4 v[220:221], off
	v_lshl_add_u64 v[220:221], s[6:7], 0, v[140:141]
	s_add_i32 m0, s81, 0xe000
	s_nop 0
	global_load_lds_dwordx4 v[220:221], off
	s_waitcnt vmcnt(8)
	s_waitcnt lgkmcnt(0)
	s_barrier
	s_waitcnt lgkmcnt(0)
	v_mfma_f32_16x16x32_bf16 v[126:129], v[146:149], v[186:189], v[126:129]
	v_mfma_f32_16x16x32_bf16 v[122:125], v[154:157], v[186:189], v[122:125]
	v_mfma_f32_16x16x32_bf16 v[118:121], v[146:149], v[194:197], v[118:121]
	v_mfma_f32_16x16x32_bf16 v[114:117], v[154:157], v[194:197], v[114:117]
	v_mfma_f32_16x16x32_bf16 v[110:113], v[146:149], v[202:205], v[110:113]
	v_mfma_f32_16x16x32_bf16 v[106:109], v[154:157], v[202:205], v[106:109]
	v_mfma_f32_16x16x32_bf16 v[102:105], v[146:149], v[212:215], v[102:105]
	v_mfma_f32_16x16x32_bf16 v[98:101], v[154:157], v[212:215], v[98:101]
	v_mfma_f32_16x16x32_bf16 v[126:129], v[150:153], v[190:193], v[126:129]
	v_mfma_f32_16x16x32_bf16 v[122:125], v[166:169], v[190:193], v[122:125]
	v_mfma_f32_16x16x32_bf16 v[118:121], v[150:153], v[198:201], v[118:121]
	v_mfma_f32_16x16x32_bf16 v[114:117], v[166:169], v[198:201], v[114:117]
	v_mfma_f32_16x16x32_bf16 v[110:113], v[150:153], v[208:211], v[110:113]
	v_mfma_f32_16x16x32_bf16 v[106:109], v[166:169], v[208:211], v[106:109]
	v_mfma_f32_16x16x32_bf16 v[102:105], v[150:153], v[216:219], v[102:105]
	v_mfma_f32_16x16x32_bf16 v[98:101], v[166:169], v[216:219], v[98:101]
	v_mfma_f32_16x16x32_bf16 v[62:65], v[170:173], v[186:189], v[62:65]
	v_mfma_f32_16x16x32_bf16 v[58:61], v[178:181], v[186:189], v[58:61]
	v_mfma_f32_16x16x32_bf16 v[54:57], v[170:173], v[194:197], v[54:57]
	v_mfma_f32_16x16x32_bf16 v[50:53], v[178:181], v[194:197], v[50:53]
	v_mfma_f32_16x16x32_bf16 v[46:49], v[170:173], v[202:205], v[46:49]
	v_mfma_f32_16x16x32_bf16 v[42:45], v[178:181], v[202:205], v[42:45]
	v_mfma_f32_16x16x32_bf16 v[38:41], v[170:173], v[212:215], v[38:41]
	v_mfma_f32_16x16x32_bf16 v[34:37], v[178:181], v[212:215], v[34:37]
	v_mfma_f32_16x16x32_bf16 v[62:65], v[174:177], v[190:193], v[62:65]
	v_mfma_f32_16x16x32_bf16 v[58:61], v[182:185], v[190:193], v[58:61]
	v_mfma_f32_16x16x32_bf16 v[54:57], v[174:177], v[198:201], v[54:57]
	v_mfma_f32_16x16x32_bf16 v[50:53], v[182:185], v[198:201], v[50:53]
	v_mfma_f32_16x16x32_bf16 v[46:49], v[174:177], v[208:211], v[46:49]
	v_mfma_f32_16x16x32_bf16 v[42:45], v[182:185], v[208:211], v[42:45]
	v_mfma_f32_16x16x32_bf16 v[38:41], v[174:177], v[216:219], v[38:41]
	v_mfma_f32_16x16x32_bf16 v[34:37], v[182:185], v[216:219], v[34:37]
	s_barrier
	s_add_i32 s85, s30, s87
	s_mov_b32 m0, s85
	ds_read_b128 v[186:189], v162 offset:16384
	ds_read_b128 v[190:193], v162 offset:17408
	ds_read_b128 v[194:197], v162 offset:18432
	ds_read_b128 v[198:201], v162 offset:19456
	ds_read_b128 v[202:205], v162 offset:20480
	ds_read_b128 v[208:211], v162 offset:21504
	ds_read_b128 v[212:215], v162 offset:22528
	ds_read_b128 v[216:219], v162 offset:23552
	global_load_lds_dwordx4 v132, s[8:9]
	s_add_i32 m0, s85, 0x2000
	s_add_u32 vcc_lo, s8, 0x40000
	v_lshl_add_u64 v[222:223], s[8:9], 0, v[136:137]
	s_addc_u32 vcc_hi, s9, 0
	s_add_i32 s85, s31, s87
	global_load_lds_dwordx4 v136, s[8:9]
	s_mov_b32 m0, s85
	v_lshl_add_u64 v[226:227], s[82:83], 0, v[134:135]
	global_load_lds_dwordx4 v132, vcc
	s_add_i32 m0, s85, 0x2000
	s_nop 0
	global_load_lds_dwordx4 v136, vcc
	v_lshl_add_u64 v[224:225], s[82:83], 0, v[130:131]
	s_mov_b32 m0, s81
	s_nop 0
	global_load_lds_dwordx4 v130, s[82:83]
	s_mov_b32 m0, s88
	s_nop 0
	global_load_lds_dwordx4 v134, s[82:83]
	s_waitcnt vmcnt(8)
	s_waitcnt lgkmcnt(0)
	s_barrier
	s_waitcnt lgkmcnt(0)
	v_mfma_f32_16x16x32_bf16 v[94:97], v[146:149], v[186:189], v[94:97]
	v_mfma_f32_16x16x32_bf16 v[90:93], v[154:157], v[186:189], v[90:93]
	v_mfma_f32_16x16x32_bf16 v[86:89], v[146:149], v[194:197], v[86:89]
	v_mfma_f32_16x16x32_bf16 v[82:85], v[154:157], v[194:197], v[82:85]
	v_mfma_f32_16x16x32_bf16 v[78:81], v[146:149], v[202:205], v[78:81]
	v_mfma_f32_16x16x32_bf16 v[74:77], v[154:157], v[202:205], v[74:77]
	v_mfma_f32_16x16x32_bf16 v[70:73], v[146:149], v[212:215], v[70:73]
	v_mfma_f32_16x16x32_bf16 v[66:69], v[154:157], v[212:215], v[66:69]
	v_mfma_f32_16x16x32_bf16 v[94:97], v[150:153], v[190:193], v[94:97]
	v_mfma_f32_16x16x32_bf16 v[90:93], v[166:169], v[190:193], v[90:93]
	v_mfma_f32_16x16x32_bf16 v[86:89], v[150:153], v[198:201], v[86:89]
	v_mfma_f32_16x16x32_bf16 v[82:85], v[166:169], v[198:201], v[82:85]
	v_mfma_f32_16x16x32_bf16 v[78:81], v[150:153], v[208:211], v[78:81]
	v_mfma_f32_16x16x32_bf16 v[74:77], v[166:169], v[208:211], v[74:77]
	v_mfma_f32_16x16x32_bf16 v[70:73], v[150:153], v[216:219], v[70:73]
	v_mfma_f32_16x16x32_bf16 v[66:69], v[166:169], v[216:219], v[66:69]
	v_mfma_f32_16x16x32_bf16 v[30:33], v[170:173], v[186:189], v[30:33]
	v_mfma_f32_16x16x32_bf16 v[26:29], v[178:181], v[186:189], v[26:29]
	v_mfma_f32_16x16x32_bf16 v[22:25], v[170:173], v[194:197], v[22:25]
	v_mfma_f32_16x16x32_bf16 v[18:21], v[178:181], v[194:197], v[18:21]
	v_mfma_f32_16x16x32_bf16 v[14:17], v[170:173], v[202:205], v[14:17]
	v_mfma_f32_16x16x32_bf16 v[10:13], v[178:181], v[202:205], v[10:13]
	v_mfma_f32_16x16x32_bf16 v[6:9], v[170:173], v[212:215], v[6:9]
	v_mfma_f32_16x16x32_bf16 v[2:5], v[178:181], v[212:215], v[2:5]
	v_mfma_f32_16x16x32_bf16 v[30:33], v[174:177], v[190:193], v[30:33]
	v_mfma_f32_16x16x32_bf16 v[26:29], v[182:185], v[190:193], v[26:29]
	v_mfma_f32_16x16x32_bf16 v[22:25], v[174:177], v[198:201], v[22:25]
	v_mfma_f32_16x16x32_bf16 v[18:21], v[182:185], v[198:201], v[18:21]
	v_mfma_f32_16x16x32_bf16 v[14:17], v[174:177], v[208:211], v[14:17]
	v_mfma_f32_16x16x32_bf16 v[10:13], v[182:185], v[208:211], v[10:13]
	v_mfma_f32_16x16x32_bf16 v[6:9], v[174:177], v[216:219], v[6:9]
	v_mfma_f32_16x16x32_bf16 v[2:5], v[182:185], v[216:219], v[2:5]
	s_barrier
; #define PG8_STAGE(bufoff, gbase, voff) do { _Pragma("unroll") for (int _i = 0; _i < 2; ++_i) \
;         __builtin_amdgcn_global_load_lds((const unsigned*)((const char*)(gbase) + (voff)[_i]), (PG8_LAS unsigned*)(lds + (bufoff) + ldsw + _i * 8192), 16, 0, 0); } while (0)
; #define PG8_LDA(dst, b, h) do { _Pragma("unroll") for (int m = 0; m < 4; ++m) _Pragma("unroll") for (int k = 0; k < 2; ++k) dst[m][k] = *(const PG8_LAS bf16x8*)(lds + PG8_SA(b, h) + aoff + m * 2048 + k * 1024); } while (0)
; #define PG8_LDB(dst, b, h) do { _Pragma("unroll") for (int n = 0; n < 2; ++n) _Pragma("unroll") for (int k = 0; k < 2; ++k) dst[n][k] = *(const PG8_LAS bf16x8*)(lds + PG8_SB(b, h) + boff + n * 2048 + k * 1024); } while (0)
; #define PG8_MMA(ai, bj, At, Bt) do { __builtin_amdgcn_s_setprio(1); _Pragma("unroll") for (int m = 0; m < 4; ++m) _Pragma("unroll") for (int n = 0; n < 2; ++n) _Pragma("unroll") for (int k = 0; k < 2; ++k) \
;         acc[ai][bj][m][n] = __builtin_amdgcn_mfma_f32_16x16x32_bf16(Bt[n][k], At[m][k], acc[ai][bj][m][n], 0, 0, 0); __builtin_amdgcn_s_setprio(0); } while (0)
; #define PG8_WAIT_V(n) asm volatile("s_waitcnt vmcnt(" #n ")" ::: "memory")
; #define PG8_WAIT_L(n) asm volatile("s_waitcnt lgkmcnt(" #n ")" ::: "memory")
; #define PG8_BAR __builtin_amdgcn_s_barrier()
; #define PG8_SCHED __builtin_amdgcn_sched_barrier(0)
; template <class Epi, class Sched, bool ALIGN_EPI = false, bool SP2 = false>
; __device__ __forceinline__ void gemm_phase(PG8_LAS unsigned char* lds, const Gemm g, const Sched& S, const Epi& E) {
;     ...
;             PG8_LDB(B0, 1, 0); PG8_LDB(B1, 1, 1); PG8_SCHED; PG8_LDA(At, 1, 0); PG8_STAGE(PG8_SA(0, 1), a2 + hstep, voffA);
;             PG8_WAIT_V(8); PG8_WAIT_L(0); PG8_BAR; PG8_MMA(0, 0, At, B0); PG8_MMA(0, 1, At, B1); PG8_BAR; PG8_SCHED;
;             PG8_LDA(At, 1, 1); PG8_STAGE(PG8_SB(1, 0), b3, voffB); PG8_STAGE(PG8_SB(1, 1), b3 + hstep, voffB); PG8_STAGE(PG8_SA(1, 0), a3, voffA);
;             PG8_WAIT_V(8); PG8_WAIT_L(0); PG8_BAR; PG8_MMA(1, 0, At, B0); PG8_MMA(1, 1, At, B1); PG8_BAR; PG8_SCHED;
	s_add_i32 s85, 0, 0x18000
	v_add_u32_e32 v165, s85, v158
	s_add_i32 vcc_lo, 0, 0x1c000
	ds_read_b128 v[146:149], v165
	ds_read_b128 v[150:153], v165 offset:1024
	ds_read_b128 v[154:157], v165 offset:2048
	ds_read_b128 v[166:169], v165 offset:3072
	v_add_u32_e32 v165, vcc_lo, v158
	ds_read_b128 v[170:173], v165
	ds_read_b128 v[174:177], v165 offset:1024
	ds_read_b128 v[178:181], v165 offset:2048
	ds_read_b128 v[182:185], v165 offset:3072
	s_add_u32 s82, s82, 0x40000
	s_addc_u32 s83, s83, 0
	s_mov_b32 m0, s89
	ds_read_b128 v[186:189], v162 offset:32768
	ds_read_b128 v[190:193], v162 offset:33792
	ds_read_b128 v[194:197], v162 offset:34816
	ds_read_b128 v[198:201], v162 offset:35840
	ds_read_b128 v[202:205], v162 offset:36864
	ds_read_b128 v[208:211], v162 offset:37888
	ds_read_b128 v[212:215], v162 offset:38912
	ds_read_b128 v[216:219], v162 offset:39936
	global_load_lds_dwordx4 v130, s[82:83]
	s_mov_b32 m0, s90
	s_nop 0
	global_load_lds_dwordx4 v134, s[82:83]
	s_waitcnt vmcnt(8)
	s_waitcnt lgkmcnt(0)
	s_barrier
	s_waitcnt lgkmcnt(0)
	v_mfma_f32_16x16x32_bf16 v[126:129], v[146:149], v[186:189], v[126:129]
	v_mfma_f32_16x16x32_bf16 v[122:125], v[154:157], v[186:189], v[122:125]
	v_mfma_f32_16x16x32_bf16 v[118:121], v[146:149], v[194:197], v[118:121]
	v_mfma_f32_16x16x32_bf16 v[114:117], v[154:157], v[194:197], v[114:117]
	v_mfma_f32_16x16x32_bf16 v[110:113], v[146:149], v[202:205], v[110:113]
	v_mfma_f32_16x16x32_bf16 v[106:109], v[154:157], v[202:205], v[106:109]
	v_mfma_f32_16x16x32_bf16 v[102:105], v[146:149], v[212:215], v[102:105]
	v_mfma_f32_16x16x32_bf16 v[98:101], v[154:157], v[212:215], v[98:101]
	v_mfma_f32_16x16x32_bf16 v[126:129], v[150:153], v[190:193], v[126:129]
	v_mfma_f32_16x16x32_bf16 v[122:125], v[166:169], v[190:193], v[122:125]
	v_mfma_f32_16x16x32_bf16 v[118:121], v[150:153], v[198:201], v[118:121]
	v_mfma_f32_16x16x32_bf16 v[114:117], v[166:169], v[198:201], v[114:117]
	v_mfma_f32_16x16x32_bf16 v[110:113], v[150:153], v[208:211], v[110:113]
	v_mfma_f32_16x16x32_bf16 v[106:109], v[166:169], v[208:211], v[106:109]
	v_mfma_f32_16x16x32_bf16 v[102:105], v[150:153], v[216:219], v[102:105]
	v_mfma_f32_16x16x32_bf16 v[98:101], v[166:169], v[216:219], v[98:101]
	v_mfma_f32_16x16x32_bf16 v[62:65], v[170:173], v[186:189], v[62:65]
	v_mfma_f32_16x16x32_bf16 v[58:61], v[178:181], v[186:189], v[58:61]
	v_mfma_f32_16x16x32_bf16 v[54:57], v[170:173], v[194:197], v[54:57]
	v_mfma_f32_16x16x32_bf16 v[50:53], v[178:181], v[194:197], v[50:53]
	v_mfma_f32_16x16x32_bf16 v[46:49], v[170:173], v[202:205], v[46:49]
	v_mfma_f32_16x16x32_bf16 v[42:45], v[178:181], v[202:205], v[42:45]
	v_mfma_f32_16x16x32_bf16 v[38:41], v[170:173], v[212:215], v[38:41]
	v_mfma_f32_16x16x32_bf16 v[34:37], v[178:181], v[212:215], v[34:37]
	v_mfma_f32_16x16x32_bf16 v[62:65], v[174:177], v[190:193], v[62:65]
	v_mfma_f32_16x16x32_bf16 v[58:61], v[182:185], v[190:193], v[58:61]
	v_mfma_f32_16x16x32_bf16 v[54:57], v[174:177], v[198:201], v[54:57]
	v_mfma_f32_16x16x32_bf16 v[50:53], v[182:185], v[198:201], v[50:53]
	v_mfma_f32_16x16x32_bf16 v[46:49], v[174:177], v[208:211], v[46:49]
	v_mfma_f32_16x16x32_bf16 v[42:45], v[182:185], v[208:211], v[42:45]
	v_mfma_f32_16x16x32_bf16 v[38:41], v[174:177], v[216:219], v[38:41]
	v_mfma_f32_16x16x32_bf16 v[34:37], v[182:185], v[216:219], v[34:37]
	s_barrier
	s_add_i32 s82, s85, s87
	s_mov_b32 m0, s82
	ds_read_b128 v[186:189], v162 offset:49152
	ds_read_b128 v[190:193], v162 offset:50176
	ds_read_b128 v[194:197], v162 offset:51200
	ds_read_b128 v[198:201], v162 offset:52224
	ds_read_b128 v[202:205], v162 offset:53248
	ds_read_b128 v[208:211], v162 offset:54272
	ds_read_b128 v[212:215], v162 offset:55296
	ds_read_b128 v[216:219], v162 offset:56320
	s_add_u32 s98, s8, s26
	s_addc_u32 s99, s9, s27
	global_load_lds_dwordx4 v132, s[98:99]
	s_add_i32 m0, s82, 0x2000
	s_add_u32 s8, s8, 0x40080
	v_lshl_add_u64 v[220:221], v[222:223], 0, s[26:27]
	s_addc_u32 s9, s9, 0
	s_add_i32 s82, vcc_lo, s87
	global_load_lds_dwordx4 v[220:221], off
	s_mov_b32 m0, s82
	s_nop 0
	global_load_lds_dwordx4 v132, s[8:9]
	s_add_i32 m0, s82, 0x2000
	s_nop 0
	global_load_lds_dwordx4 v136, s[8:9]
	v_lshl_add_u64 v[220:221], v[224:225], 0, s[26:27]
	s_mov_b32 m0, s92
	s_nop 0
	global_load_lds_dwordx4 v[220:221], off
	v_lshl_add_u64 v[220:221], v[226:227], 0, s[26:27]
	s_mov_b32 m0, s93
	s_nop 0
	global_load_lds_dwordx4 v[220:221], off
	s_waitcnt vmcnt(8)
	s_waitcnt lgkmcnt(0)
	s_barrier
	s_waitcnt lgkmcnt(0)
	v_mfma_f32_16x16x32_bf16 v[94:97], v[146:149], v[186:189], v[94:97]
	v_mfma_f32_16x16x32_bf16 v[90:93], v[154:157], v[186:189], v[90:93]
	v_mfma_f32_16x16x32_bf16 v[86:89], v[146:149], v[194:197], v[86:89]
	v_mfma_f32_16x16x32_bf16 v[82:85], v[154:157], v[194:197], v[82:85]
	v_mfma_f32_16x16x32_bf16 v[78:81], v[146:149], v[202:205], v[78:81]
	v_mfma_f32_16x16x32_bf16 v[74:77], v[154:157], v[202:205], v[74:77]
	v_mfma_f32_16x16x32_bf16 v[70:73], v[146:149], v[212:215], v[70:73]
	v_mfma_f32_16x16x32_bf16 v[66:69], v[154:157], v[212:215], v[66:69]
	v_mfma_f32_16x16x32_bf16 v[94:97], v[150:153], v[190:193], v[94:97]
	v_mfma_f32_16x16x32_bf16 v[90:93], v[166:169], v[190:193], v[90:93]
	v_mfma_f32_16x16x32_bf16 v[86:89], v[150:153], v[198:201], v[86:89]
	v_mfma_f32_16x16x32_bf16 v[82:85], v[166:169], v[198:201], v[82:85]
	v_mfma_f32_16x16x32_bf16 v[78:81], v[150:153], v[208:211], v[78:81]
	v_mfma_f32_16x16x32_bf16 v[74:77], v[166:169], v[208:211], v[74:77]
	v_mfma_f32_16x16x32_bf16 v[70:73], v[150:153], v[216:219], v[70:73]
	v_mfma_f32_16x16x32_bf16 v[66:69], v[166:169], v[216:219], v[66:69]
	v_mfma_f32_16x16x32_bf16 v[30:33], v[170:173], v[186:189], v[30:33]
	v_mfma_f32_16x16x32_bf16 v[26:29], v[178:181], v[186:189], v[26:29]
	v_mfma_f32_16x16x32_bf16 v[22:25], v[170:173], v[194:197], v[22:25]
	v_mfma_f32_16x16x32_bf16 v[18:21], v[178:181], v[194:197], v[18:21]
	v_mfma_f32_16x16x32_bf16 v[14:17], v[170:173], v[202:205], v[14:17]
	v_mfma_f32_16x16x32_bf16 v[10:13], v[178:181], v[202:205], v[10:13]
	v_mfma_f32_16x16x32_bf16 v[6:9], v[170:173], v[212:215], v[6:9]
	v_mfma_f32_16x16x32_bf16 v[2:5], v[178:181], v[212:215], v[2:5]
	v_mfma_f32_16x16x32_bf16 v[30:33], v[174:177], v[190:193], v[30:33]
	v_mfma_f32_16x16x32_bf16 v[26:29], v[182:185], v[190:193], v[26:29]
	v_mfma_f32_16x16x32_bf16 v[22:25], v[174:177], v[198:201], v[22:25]
	v_mfma_f32_16x16x32_bf16 v[18:21], v[182:185], v[198:201], v[18:21]
	v_mfma_f32_16x16x32_bf16 v[14:17], v[174:177], v[208:211], v[14:17]
	v_mfma_f32_16x16x32_bf16 v[10:13], v[182:185], v[208:211], v[10:13]
	v_mfma_f32_16x16x32_bf16 v[6:9], v[174:177], v[216:219], v[6:9]
	v_mfma_f32_16x16x32_bf16 v[2:5], v[182:185], v[216:219], v[2:5]
	s_add_i32 s84, s84, 2
	s_add_u32 s6, s6, 0x100
	s_addc_u32 s7, s7, 0
	s_add_u32 s73, s73, 0x100
	s_addc_u32 s75, s75, 0
	s_cmp_gt_u32 s84, 13
	s_barrier
	s_cbranch_scc0 .LBB0_110
	s_setprio 0
	s_mov_b32 s100, 0xbfb8aa3b
	s_mov_b32 s98, 1.0
	s_and_b64 vcc, exec, s[68:69]
	s_cbranch_vccz .LBB0_113
	s_barrier

; #define PG8_STAGE(bufoff, gbase, voff) do { _Pragma("unroll") for (int _i = 0; _i < 2; ++_i) \
;         __builtin_amdgcn_global_load_lds((const unsigned*)((const char*)(gbase) + (voff)[_i]), (PG8_LAS unsigned*)(lds + (bufoff) + ldsw + _i * 8192), 16, 0, 0); } while (0)
; #define PG8_LDA(dst, b, h) do { _Pragma("unroll") for (int m = 0; m < 4; ++m) _Pragma("unroll") for (int k = 0; k < 2; ++k) dst[m][k] = *(const PG8_LAS bf16x8*)(lds + PG8_SA(b, h) + aoff + m * 2048 + k * 1024); } while (0)
; #define PG8_LDB(dst, b, h) do { _Pragma("unroll") for (int n = 0; n < 2; ++n) _Pragma("unroll") for (int k = 0; k < 2; ++k) dst[n][k] = *(const PG8_LAS bf16x8*)(lds + PG8_SB(b, h) + boff + n * 2048 + k * 1024); } while (0)
; #define PG8_WAIT_V(n) asm volatile("s_waitcnt vmcnt(" #n ")" ::: "memory")
; #define PG8_WAIT_L(n) asm volatile("s_waitcnt lgkmcnt(" #n ")" ::: "memory")
; #define PG8_BAR __builtin_amdgcn_s_barrier()
; #define PG8_SCHED __builtin_amdgcn_sched_barrier(0)
; template <class Epi, class Sched, bool ALIGN_EPI = false, bool SP2 = false>
; __device__ __forceinline__ void gemm_phase(PG8_LAS unsigned char* lds, const Gemm g, const Sched& S, const Epi& E) {
;     ...
;         const bool has_next = S.next(ui + 1, nxt);
;         const char* nA = has_next ? (const char*)g.A + (size_t)nxt.pm * tstep : cA; const char* nB = has_next ? (const char*)g.Bt + (size_t)nxt.pn * tstep : cB;
;         for (int t = 0; t < nt; t += 2) {
;             const bool last = (t == nt - 2);
;             const char* a1 = cA + (size_t)(t + 1) * kstep;
;             const char* a2 = last ? nA : cA + (size_t)(t + 2) * kstep; const char* b2 = last ? nB : cB + (size_t)(t + 2) * kstep;
;             const char* a3 = a2 + kstep; const char* b3 = b2 + kstep;
;             if (last && has_next) S.a_ready(nxt);
;             if constexpr (SP2) {
;             PG8_LDB(B0, 0, 0); PG8_LDB(B1, 0, 1); PG8_SCHED; PG8_LDA(At, 0, 0); PG8_STAGE(PG8_SA(1, 1), a1 + hstep, voffA);
;             PG8_WAIT_V(8); PG8_WAIT_L(0); PG8_BAR; PG8_MMA(0, 0, At, B0); PG8_MMA(0, 1, At, B1); PG8_BAR; PG8_SCHED;
;             PG8_LDA(At, 0, 1); PG8_STAGE(PG8_SB(0, 0), b2, voffB); PG8_STAGE(PG8_SB(0, 1), b2 + hstep, voffB); PG8_STAGE(PG8_SA(0, 0), a2, voffA);
;             PG8_WAIT_V(8); PG8_WAIT_L(0); PG8_BAR; PG8_MMA(1, 0, At, B0); PG8_MMA(1, 1, At, B1); PG8_BAR; PG8_SCHED;
.LBB0_645:
	s_ashr_i32 s21, s20, 31
	s_lshl_b64 s[22:23], s[20:21], 19
	s_add_u32 s22, s0, s22
	s_addc_u32 s23, s1, s23
	s_and_b64 s[24:25], s[6:7], exec
	s_cselect_b32 s21, s23, s45
	s_cselect_b32 s27, s22, s44
	s_ashr_i32 s19, s18, 31
	s_lshl_b64 s[24:25], s[18:19], 19
	s_add_u32 s24, s64, s24
	s_addc_u32 s25, s65, s25
	s_and_b64 s[48:49], s[6:7], exec
	s_cselect_b32 s19, s25, s47
	s_cselect_b32 s33, s24, s46
	s_add_u32 s44, s44, 0x40080
	s_addc_u32 s45, s45, 0
	s_add_u32 s71, s46, 0x100
	s_addc_u32 s72, s47, 0
	s_mov_b32 s73, -2
	s_waitcnt lgkmcnt(0)
	s_bitcmp1_b32 s16, 0
	s_cbranch_scc1 .Lnp_646
	s_setprio 1
.Lnp_646:
	ds_read_b128 v[148:151], v152
	ds_read_b128 v[156:159], v152 offset:1024
	ds_read_b128 v[160:163], v152 offset:2048
	ds_read_b128 v[164:167], v152 offset:3072
	ds_read_b128 v[168:171], v153
	ds_read_b128 v[172:175], v153 offset:1024
	ds_read_b128 v[176:179], v153 offset:2048
	ds_read_b128 v[180:183], v153 offset:3072
	s_add_u32 s46, s44, 0xfffc0080
	s_addc_u32 s47, s45, -1
	s_cmp_eq_u32 s73, 12
	s_cselect_b32 s49, s21, s47
	s_cselect_b32 s48, s27, s46
	s_cselect_b32 s47, s19, s72
	s_cselect_b32 s46, s33, s71
	v_lshl_add_u64 v[204:205], s[44:45], 0, v[140:141]
	s_add_i32 m0, s31, 0xc000
	ds_read_b128 v[184:187], v154
	ds_read_b128 v[188:191], v154 offset:1024
	ds_read_b128 v[192:195], v154 offset:2048
	ds_read_b128 v[196:199], v154 offset:3072
	ds_read_b128 v[200:203], v154 offset:4096
	ds_read_b128 v[208:211], v154 offset:5120
	ds_read_b128 v[212:215], v154 offset:6144
	ds_read_b128 v[216:219], v154 offset:7168
	global_load_lds_dwordx4 v[204:205], off
	v_lshl_add_u64 v[204:205], s[44:45], 0, v[142:143]
	s_add_i32 m0, s31, 0xe000
	s_nop 0
	global_load_lds_dwordx4 v[204:205], off
	s_waitcnt vmcnt(8)
	s_waitcnt lgkmcnt(0)
	s_barrier
	s_waitcnt lgkmcnt(0)
	v_mfma_f32_16x16x32_bf16 v[126:129], v[148:151], v[184:187], 0
	v_mfma_f32_16x16x32_bf16 v[122:125], v[160:163], v[184:187], 0
	v_mfma_f32_16x16x32_bf16 v[110:113], v[148:151], v[192:195], 0
	v_mfma_f32_16x16x32_bf16 v[106:109], v[160:163], v[192:195], 0
	v_mfma_f32_16x16x32_bf16 v[94:97], v[148:151], v[200:203], 0
	v_mfma_f32_16x16x32_bf16 v[90:93], v[160:163], v[200:203], 0
	v_mfma_f32_16x16x32_bf16 v[78:81], v[148:151], v[212:215], 0
	v_mfma_f32_16x16x32_bf16 v[74:77], v[160:163], v[212:215], 0
	v_mfma_f32_16x16x32_bf16 v[126:129], v[156:159], v[188:191], v[126:129]
	v_mfma_f32_16x16x32_bf16 v[122:125], v[164:167], v[188:191], v[122:125]
	v_mfma_f32_16x16x32_bf16 v[110:113], v[156:159], v[196:199], v[110:113]
	v_mfma_f32_16x16x32_bf16 v[106:109], v[164:167], v[196:199], v[106:109]
	v_mfma_f32_16x16x32_bf16 v[94:97], v[156:159], v[208:211], v[94:97]
	v_mfma_f32_16x16x32_bf16 v[90:93], v[164:167], v[208:211], v[90:93]
	v_mfma_f32_16x16x32_bf16 v[78:81], v[156:159], v[216:219], v[78:81]
	v_mfma_f32_16x16x32_bf16 v[74:77], v[164:167], v[216:219], v[74:77]
	v_mfma_f32_16x16x32_bf16 v[118:121], v[168:171], v[184:187], 0
	v_mfma_f32_16x16x32_bf16 v[114:117], v[176:179], v[184:187], 0
	v_mfma_f32_16x16x32_bf16 v[102:105], v[168:171], v[192:195], 0
	v_mfma_f32_16x16x32_bf16 v[98:101], v[176:179], v[192:195], 0
	v_mfma_f32_16x16x32_bf16 v[86:89], v[168:171], v[200:203], 0
	v_mfma_f32_16x16x32_bf16 v[82:85], v[176:179], v[200:203], 0
	v_mfma_f32_16x16x32_bf16 v[70:73], v[168:171], v[212:215], 0
	v_mfma_f32_16x16x32_bf16 v[66:69], v[176:179], v[212:215], 0
	v_mfma_f32_16x16x32_bf16 v[118:121], v[172:175], v[188:191], v[118:121]
	v_mfma_f32_16x16x32_bf16 v[114:117], v[180:183], v[188:191], v[114:117]
	v_mfma_f32_16x16x32_bf16 v[102:105], v[172:175], v[196:199], v[102:105]
	v_mfma_f32_16x16x32_bf16 v[98:101], v[180:183], v[196:199], v[98:101]
	v_mfma_f32_16x16x32_bf16 v[86:89], v[172:175], v[208:211], v[86:89]
	v_mfma_f32_16x16x32_bf16 v[82:85], v[180:183], v[208:211], v[82:85]
	v_mfma_f32_16x16x32_bf16 v[70:73], v[172:175], v[216:219], v[70:73]
	v_mfma_f32_16x16x32_bf16 v[66:69], v[180:183], v[216:219], v[66:69]
	s_barrier
	s_add_i32 s74, s68, s30
	s_mov_b32 m0, s74
	ds_read_b128 v[184:187], v154 offset:16384
	ds_read_b128 v[188:191], v154 offset:17408
	ds_read_b128 v[192:195], v154 offset:18432
	ds_read_b128 v[196:199], v154 offset:19456
	ds_read_b128 v[200:203], v154 offset:20480
	ds_read_b128 v[208:211], v154 offset:21504
	ds_read_b128 v[212:215], v154 offset:22528
	ds_read_b128 v[216:219], v154 offset:23552
	global_load_lds_dwordx4 v132, s[46:47]
	s_add_i32 m0, s74, 0x2000
	s_add_u32 s74, s46, 0x40000
	v_lshl_add_u64 v[220:221], s[46:47], 0, v[136:137]
	s_addc_u32 s75, s47, 0
	s_add_i32 s76, s69, s30
	global_load_lds_dwordx4 v136, s[46:47]
	s_mov_b32 m0, s76
	v_lshl_add_u64 v[224:225], s[48:49], 0, v[134:135]
	global_load_lds_dwordx4 v132, s[74:75]
	s_add_i32 m0, s76, 0x2000
	s_nop 0
	global_load_lds_dwordx4 v136, s[74:75]
	v_lshl_add_u64 v[222:223], s[48:49], 0, v[130:131]
	s_mov_b32 m0, s31
	s_nop 0
	global_load_lds_dwordx4 v130, s[48:49]
	s_mov_b32 m0, s50
	s_nop 0
	global_load_lds_dwordx4 v134, s[48:49]
	s_waitcnt vmcnt(8)
	s_waitcnt lgkmcnt(0)
	s_barrier
; #define PG8_STAGE(bufoff, gbase, voff) do { _Pragma("unroll") for (int _i = 0; _i < 2; ++_i) \
;         __builtin_amdgcn_global_load_lds((const unsigned*)((const char*)(gbase) + (voff)[_i]), (PG8_LAS unsigned*)(lds + (bufoff) + ldsw + _i * 8192), 16, 0, 0); } while (0)
; #define PG8_LDA(dst, b, h) do { _Pragma("unroll") for (int m = 0; m < 4; ++m) _Pragma("unroll") for (int k = 0; k < 2; ++k) dst[m][k] = *(const PG8_LAS bf16x8*)(lds + PG8_SA(b, h) + aoff + m * 2048 + k * 1024); } while (0)
; #define PG8_LDB(dst, b, h) do { _Pragma("unroll") for (int n = 0; n < 2; ++n) _Pragma("unroll") for (int k = 0; k < 2; ++k) dst[n][k] = *(const PG8_LAS bf16x8*)(lds + PG8_SB(b, h) + boff + n * 2048 + k * 1024); } while (0)
; #define PG8_MMA(ai, bj, At, Bt) do { __builtin_amdgcn_s_setprio(1); _Pragma("unroll") for (int m = 0; m < 4; ++m) _Pragma("unroll") for (int n = 0; n < 2; ++n) _Pragma("unroll") for (int k = 0; k < 2; ++k) \
;         acc[ai][bj][m][n] = __builtin_amdgcn_mfma_f32_16x16x32_bf16(Bt[n][k], At[m][k], acc[ai][bj][m][n], 0, 0, 0); __builtin_amdgcn_s_setprio(0); } while (0)
; #define PG8_WAIT_V(n) asm volatile("s_waitcnt vmcnt(" #n ")" ::: "memory")
; #define PG8_WAIT_L(n) asm volatile("s_waitcnt lgkmcnt(" #n ")" ::: "memory")
; #define PG8_BAR __builtin_amdgcn_s_barrier()
; #define PG8_SCHED __builtin_amdgcn_sched_barrier(0)
; template <class Epi, class Sched, bool ALIGN_EPI = false, bool SP2 = false>
; __device__ __forceinline__ void gemm_phase(PG8_LAS unsigned char* lds, const Gemm g, const Sched& S, const Epi& E) {
;     ...
;             PG8_WAIT_V(8); PG8_WAIT_L(0); PG8_BAR; PG8_MMA(0, 0, At, B0); PG8_MMA(0, 1, At, B1); PG8_BAR; PG8_SCHED;
;             PG8_LDA(At, 0, 1); PG8_STAGE(PG8_SB(0, 0), b2, voffB); PG8_STAGE(PG8_SB(0, 1), b2 + hstep, voffB); PG8_STAGE(PG8_SA(0, 0), a2, voffA);
;             PG8_WAIT_V(8); PG8_WAIT_L(0); PG8_BAR; PG8_MMA(1, 0, At, B0); PG8_MMA(1, 1, At, B1); PG8_BAR; PG8_SCHED;
;             PG8_LDB(B0, 1, 0); PG8_LDB(B1, 1, 1); PG8_SCHED; PG8_LDA(At, 1, 0); PG8_STAGE(PG8_SA(0, 1), a2 + hstep, voffA);
;             PG8_WAIT_V(8); PG8_WAIT_L(0); PG8_BAR; PG8_MMA(0, 0, At, B0); PG8_MMA(0, 1, At, B1); PG8_BAR; PG8_SCHED;
	s_waitcnt lgkmcnt(0)
	v_mfma_f32_16x16x32_bf16 v[62:65], v[148:151], v[184:187], 0
	v_mfma_f32_16x16x32_bf16 v[58:61], v[160:163], v[184:187], 0
	v_mfma_f32_16x16x32_bf16 v[46:49], v[148:151], v[192:195], 0
	v_mfma_f32_16x16x32_bf16 v[42:45], v[160:163], v[192:195], 0
	v_mfma_f32_16x16x32_bf16 v[30:33], v[148:151], v[200:203], 0
	v_mfma_f32_16x16x32_bf16 v[26:29], v[160:163], v[200:203], 0
	v_mfma_f32_16x16x32_bf16 v[14:17], v[148:151], v[212:215], 0
	v_mfma_f32_16x16x32_bf16 v[10:13], v[160:163], v[212:215], 0
	v_mfma_f32_16x16x32_bf16 v[62:65], v[156:159], v[188:191], v[62:65]
	v_mfma_f32_16x16x32_bf16 v[58:61], v[164:167], v[188:191], v[58:61]
	v_mfma_f32_16x16x32_bf16 v[46:49], v[156:159], v[196:199], v[46:49]
	v_mfma_f32_16x16x32_bf16 v[42:45], v[164:167], v[196:199], v[42:45]
	v_mfma_f32_16x16x32_bf16 v[30:33], v[156:159], v[208:211], v[30:33]
	v_mfma_f32_16x16x32_bf16 v[26:29], v[164:167], v[208:211], v[26:29]
	v_mfma_f32_16x16x32_bf16 v[14:17], v[156:159], v[216:219], v[14:17]
	v_mfma_f32_16x16x32_bf16 v[10:13], v[164:167], v[216:219], v[10:13]
	v_mfma_f32_16x16x32_bf16 v[54:57], v[168:171], v[184:187], 0
	v_mfma_f32_16x16x32_bf16 v[50:53], v[176:179], v[184:187], 0
	v_mfma_f32_16x16x32_bf16 v[38:41], v[168:171], v[192:195], 0
	v_mfma_f32_16x16x32_bf16 v[34:37], v[176:179], v[192:195], 0
	v_mfma_f32_16x16x32_bf16 v[22:25], v[168:171], v[200:203], 0
	v_mfma_f32_16x16x32_bf16 v[18:21], v[176:179], v[200:203], 0
	v_mfma_f32_16x16x32_bf16 v[6:9], v[168:171], v[212:215], 0
	v_mfma_f32_16x16x32_bf16 v[2:5], v[176:179], v[212:215], 0
	v_mfma_f32_16x16x32_bf16 v[54:57], v[172:175], v[188:191], v[54:57]
	v_mfma_f32_16x16x32_bf16 v[50:53], v[180:183], v[188:191], v[50:53]
	v_mfma_f32_16x16x32_bf16 v[38:41], v[172:175], v[196:199], v[38:41]
	v_mfma_f32_16x16x32_bf16 v[34:37], v[180:183], v[196:199], v[34:37]
	v_mfma_f32_16x16x32_bf16 v[22:25], v[172:175], v[208:211], v[22:25]
	v_mfma_f32_16x16x32_bf16 v[18:21], v[180:183], v[208:211], v[18:21]
	v_mfma_f32_16x16x32_bf16 v[6:9], v[172:175], v[216:219], v[6:9]
	v_mfma_f32_16x16x32_bf16 v[2:5], v[180:183], v[216:219], v[2:5]
	s_barrier
	s_add_i32 s74, 0, 0x18000
	s_add_i32 s75, 0, 0x1c000
	v_add_u32_e32 v164, s74, v139
	v_add_u32_e32 v180, s75, v139
	ds_read_b128 v[148:151], v164
	ds_read_b128 v[156:159], v164 offset:1024
	ds_read_b128 v[160:163], v164 offset:2048
	ds_read_b128 v[164:167], v164 offset:3072
	ds_read_b128 v[168:171], v180
	ds_read_b128 v[172:175], v180 offset:1024
	ds_read_b128 v[176:179], v180 offset:2048
	ds_read_b128 v[180:183], v180 offset:3072
	s_add_u32 s48, s48, 0x40000
	s_addc_u32 s49, s49, 0
	s_mov_b32 m0, s51
	ds_read_b128 v[184:187], v154 offset:32768
	ds_read_b128 v[188:191], v154 offset:33792
	ds_read_b128 v[192:195], v154 offset:34816
	ds_read_b128 v[196:199], v154 offset:35840
	ds_read_b128 v[200:203], v154 offset:36864
	ds_read_b128 v[208:211], v154 offset:37888
	ds_read_b128 v[212:215], v154 offset:38912
	ds_read_b128 v[216:219], v154 offset:39936
	global_load_lds_dwordx4 v130, s[48:49]
	s_mov_b32 m0, s60
	s_nop 0
	global_load_lds_dwordx4 v134, s[48:49]
	s_waitcnt vmcnt(8)
	s_waitcnt lgkmcnt(0)
	s_barrier
	s_waitcnt lgkmcnt(0)
	v_mfma_f32_16x16x32_bf16 v[126:129], v[148:151], v[184:187], v[126:129]
	v_mfma_f32_16x16x32_bf16 v[122:125], v[160:163], v[184:187], v[122:125]
	v_mfma_f32_16x16x32_bf16 v[110:113], v[148:151], v[192:195], v[110:113]
	v_mfma_f32_16x16x32_bf16 v[106:109], v[160:163], v[192:195], v[106:109]
	v_mfma_f32_16x16x32_bf16 v[94:97], v[148:151], v[200:203], v[94:97]
	v_mfma_f32_16x16x32_bf16 v[90:93], v[160:163], v[200:203], v[90:93]
	v_mfma_f32_16x16x32_bf16 v[78:81], v[148:151], v[212:215], v[78:81]
	v_mfma_f32_16x16x32_bf16 v[74:77], v[160:163], v[212:215], v[74:77]
	v_mfma_f32_16x16x32_bf16 v[126:129], v[156:159], v[188:191], v[126:129]
	v_mfma_f32_16x16x32_bf16 v[122:125], v[164:167], v[188:191], v[122:125]
	v_mfma_f32_16x16x32_bf16 v[110:113], v[156:159], v[196:199], v[110:113]
	v_mfma_f32_16x16x32_bf16 v[106:109], v[164:167], v[196:199], v[106:109]
	v_mfma_f32_16x16x32_bf16 v[94:97], v[156:159], v[208:211], v[94:97]
	v_mfma_f32_16x16x32_bf16 v[90:93], v[164:167], v[208:211], v[90:93]
	v_mfma_f32_16x16x32_bf16 v[78:81], v[156:159], v[216:219], v[78:81]
	v_mfma_f32_16x16x32_bf16 v[74:77], v[164:167], v[216:219], v[74:77]
	v_mfma_f32_16x16x32_bf16 v[118:121], v[168:171], v[184:187], v[118:121]
	v_mfma_f32_16x16x32_bf16 v[114:117], v[176:179], v[184:187], v[114:117]
	v_mfma_f32_16x16x32_bf16 v[102:105], v[168:171], v[192:195], v[102:105]
	v_mfma_f32_16x16x32_bf16 v[98:101], v[176:179], v[192:195], v[98:101]
	v_mfma_f32_16x16x32_bf16 v[86:89], v[168:171], v[200:203], v[86:89]
	v_mfma_f32_16x16x32_bf16 v[82:85], v[176:179], v[200:203], v[82:85]
	v_mfma_f32_16x16x32_bf16 v[70:73], v[168:171], v[212:215], v[70:73]
	v_mfma_f32_16x16x32_bf16 v[66:69], v[176:179], v[212:215], v[66:69]
	v_mfma_f32_16x16x32_bf16 v[118:121], v[172:175], v[188:191], v[118:121]
	v_mfma_f32_16x16x32_bf16 v[114:117], v[180:183], v[188:191], v[114:117]
	v_mfma_f32_16x16x32_bf16 v[102:105], v[172:175], v[196:199], v[102:105]
	v_mfma_f32_16x16x32_bf16 v[98:101], v[180:183], v[196:199], v[98:101]
	v_mfma_f32_16x16x32_bf16 v[86:89], v[172:175], v[208:211], v[86:89]
	v_mfma_f32_16x16x32_bf16 v[82:85], v[180:183], v[208:211], v[82:85]
	v_mfma_f32_16x16x32_bf16 v[70:73], v[172:175], v[216:219], v[70:73]
	v_mfma_f32_16x16x32_bf16 v[66:69], v[180:183], v[216:219], v[66:69]
	s_barrier
; #define PG8_STAGE(bufoff, gbase, voff) do { _Pragma("unroll") for (int _i = 0; _i < 2; ++_i) \
;         __builtin_amdgcn_global_load_lds((const unsigned*)((const char*)(gbase) + (voff)[_i]), (PG8_LAS unsigned*)(lds + (bufoff) + ldsw + _i * 8192), 16, 0, 0); } while (0)
; #define PG8_LDA(dst, b, h) do { _Pragma("unroll") for (int m = 0; m < 4; ++m) _Pragma("unroll") for (int k = 0; k < 2; ++k) dst[m][k] = *(const PG8_LAS bf16x8*)(lds + PG8_SA(b, h) + aoff + m * 2048 + k * 1024); } while (0)
; #define PG8_LDB(dst, b, h) do { _Pragma("unroll") for (int n = 0; n < 2; ++n) _Pragma("unroll") for (int k = 0; k < 2; ++k) dst[n][k] = *(const PG8_LAS bf16x8*)(lds + PG8_SB(b, h) + boff + n * 2048 + k * 1024); } while (0)
; #define PG8_MMA(ai, bj, At, Bt) do { __builtin_amdgcn_s_setprio(1); _Pragma("unroll") for (int m = 0; m < 4; ++m) _Pragma("unroll") for (int n = 0; n < 2; ++n) _Pragma("unroll") for (int k = 0; k < 2; ++k) \
;         acc[ai][bj][m][n] = __builtin_amdgcn_mfma_f32_16x16x32_bf16(Bt[n][k], At[m][k], acc[ai][bj][m][n], 0, 0, 0); __builtin_amdgcn_s_setprio(0); } while (0)
; #define PG8_WAIT_V(n) asm volatile("s_waitcnt vmcnt(" #n ")" ::: "memory")
; #define PG8_WAIT_L(n) asm volatile("s_waitcnt lgkmcnt(" #n ")" ::: "memory")
; #define PG8_BAR __builtin_amdgcn_s_barrier()
; #define PG8_SCHED __builtin_amdgcn_sched_barrier(0)
; template <class Epi, class Sched, bool ALIGN_EPI = false, bool SP2 = false>
; __device__ __forceinline__ void gemm_phase(PG8_LAS unsigned char* lds, const Gemm g, const Sched& S, const Epi& E) {
;     ...
;             PG8_LDB(B0, 0, 0); PG8_LDB(B1, 0, 1); PG8_SCHED; PG8_LDA(At, 0, 0); PG8_STAGE(PG8_SA(1, 1), a1 + hstep, voffA);
;             PG8_WAIT_V(8); PG8_WAIT_L(0); PG8_BAR; PG8_MMA(0, 0, At, B0); PG8_MMA(0, 1, At, B1); PG8_BAR; PG8_SCHED;
;     ...
;             PG8_LDA(At, 1, 1); PG8_STAGE(PG8_SB(1, 0), b3, voffB); PG8_STAGE(PG8_SB(1, 1), b3 + hstep, voffB); PG8_STAGE(PG8_SA(1, 0), a3, voffA);
;             PG8_WAIT_V(8); PG8_WAIT_L(0); PG8_BAR; PG8_MMA(1, 0, At, B0); PG8_MMA(1, 1, At, B1); PG8_BAR; PG8_SCHED;
	s_add_i32 s48, s74, s30
	s_mov_b32 m0, s48
	ds_read_b128 v[184:187], v154 offset:49152
	ds_read_b128 v[188:191], v154 offset:50176
	ds_read_b128 v[192:195], v154 offset:51200
	ds_read_b128 v[196:199], v154 offset:52224
	ds_read_b128 v[200:203], v154 offset:53248
	ds_read_b128 v[208:211], v154 offset:54272
	ds_read_b128 v[212:215], v154 offset:55296
	ds_read_b128 v[216:219], v154 offset:56320
	s_add_u32 s98, s46, s14
	s_addc_u32 s99, s47, s15
	global_load_lds_dwordx4 v132, s[98:99]
	s_add_i32 m0, s48, 0x2000
	s_add_u32 s46, s46, 0x40080
	v_lshl_add_u64 v[204:205], v[220:221], 0, s[14:15]
	s_addc_u32 s47, s47, 0
	s_add_i32 s48, s75, s30
	global_load_lds_dwordx4 v[204:205], off
	s_mov_b32 m0, s48
	s_nop 0
	global_load_lds_dwordx4 v132, s[46:47]
	s_add_i32 m0, s48, 0x2000
	s_nop 0
	global_load_lds_dwordx4 v136, s[46:47]
	v_lshl_add_u64 v[204:205], v[222:223], 0, s[14:15]
	s_mov_b32 m0, s62
	s_nop 0
	global_load_lds_dwordx4 v[204:205], off
	v_lshl_add_u64 v[204:205], v[224:225], 0, s[14:15]
	s_mov_b32 m0, s63
	s_nop 0
	global_load_lds_dwordx4 v[204:205], off
	s_waitcnt vmcnt(8)
	s_waitcnt lgkmcnt(0)
	s_barrier
	s_waitcnt lgkmcnt(0)
	v_mfma_f32_16x16x32_bf16 v[62:65], v[148:151], v[184:187], v[62:65]
	v_mfma_f32_16x16x32_bf16 v[58:61], v[160:163], v[184:187], v[58:61]
	v_mfma_f32_16x16x32_bf16 v[46:49], v[148:151], v[192:195], v[46:49]
	v_mfma_f32_16x16x32_bf16 v[42:45], v[160:163], v[192:195], v[42:45]
	v_mfma_f32_16x16x32_bf16 v[30:33], v[148:151], v[200:203], v[30:33]
	v_mfma_f32_16x16x32_bf16 v[26:29], v[160:163], v[200:203], v[26:29]
	v_mfma_f32_16x16x32_bf16 v[14:17], v[148:151], v[212:215], v[14:17]
	v_mfma_f32_16x16x32_bf16 v[10:13], v[160:163], v[212:215], v[10:13]
	v_mfma_f32_16x16x32_bf16 v[62:65], v[156:159], v[188:191], v[62:65]
	v_mfma_f32_16x16x32_bf16 v[58:61], v[164:167], v[188:191], v[58:61]
	v_mfma_f32_16x16x32_bf16 v[46:49], v[156:159], v[196:199], v[46:49]
	v_mfma_f32_16x16x32_bf16 v[42:45], v[164:167], v[196:199], v[42:45]
	v_mfma_f32_16x16x32_bf16 v[30:33], v[156:159], v[208:211], v[30:33]
	v_mfma_f32_16x16x32_bf16 v[26:29], v[164:167], v[208:211], v[26:29]
	v_mfma_f32_16x16x32_bf16 v[14:17], v[156:159], v[216:219], v[14:17]
	v_mfma_f32_16x16x32_bf16 v[10:13], v[164:167], v[216:219], v[10:13]
	v_mfma_f32_16x16x32_bf16 v[54:57], v[168:171], v[184:187], v[54:57]
	v_mfma_f32_16x16x32_bf16 v[50:53], v[176:179], v[184:187], v[50:53]
	v_mfma_f32_16x16x32_bf16 v[38:41], v[168:171], v[192:195], v[38:41]
	v_mfma_f32_16x16x32_bf16 v[34:37], v[176:179], v[192:195], v[34:37]
	v_mfma_f32_16x16x32_bf16 v[22:25], v[168:171], v[200:203], v[22:25]
	v_mfma_f32_16x16x32_bf16 v[18:21], v[176:179], v[200:203], v[18:21]
	v_mfma_f32_16x16x32_bf16 v[6:9], v[168:171], v[212:215], v[6:9]
	v_mfma_f32_16x16x32_bf16 v[2:5], v[176:179], v[212:215], v[2:5]
	v_mfma_f32_16x16x32_bf16 v[54:57], v[172:175], v[188:191], v[54:57]
	v_mfma_f32_16x16x32_bf16 v[50:53], v[180:183], v[188:191], v[50:53]
	v_mfma_f32_16x16x32_bf16 v[38:41], v[172:175], v[196:199], v[38:41]
	v_mfma_f32_16x16x32_bf16 v[34:37], v[180:183], v[196:199], v[34:37]
	v_mfma_f32_16x16x32_bf16 v[22:25], v[172:175], v[208:211], v[22:25]
	v_mfma_f32_16x16x32_bf16 v[18:21], v[180:183], v[208:211], v[18:21]
	v_mfma_f32_16x16x32_bf16 v[6:9], v[172:175], v[216:219], v[6:9]
	v_mfma_f32_16x16x32_bf16 v[2:5], v[180:183], v[216:219], v[2:5]
	s_add_i32 s73, s73, 2
	s_add_u32 s44, s44, 0x100
	s_addc_u32 s45, s45, 0
	s_add_u32 s71, s71, 0x100
	s_addc_u32 s72, s72, 0
	s_cmp_gt_u32 s73, 13
	s_barrier
.LBB0_646:
	ds_read_b128 v[148:151], v152
	ds_read_b128 v[156:159], v152 offset:1024
	ds_read_b128 v[160:163], v152 offset:2048
	ds_read_b128 v[164:167], v152 offset:3072
	ds_read_b128 v[168:171], v153
	ds_read_b128 v[172:175], v153 offset:1024
	ds_read_b128 v[176:179], v153 offset:2048
	ds_read_b128 v[180:183], v153 offset:3072
	s_add_u32 s46, s44, 0xfffc0080
	s_addc_u32 s47, s45, -1
	s_cmp_eq_u32 s73, 12
	s_cselect_b32 s49, s21, s47
	s_cselect_b32 s48, s27, s46
	s_cselect_b32 s47, s19, s72
	s_cselect_b32 s46, s33, s71
	v_lshl_add_u64 v[204:205], s[44:45], 0, v[140:141]
	s_add_i32 m0, s31, 0xc000
	ds_read_b128 v[184:187], v154
	ds_read_b128 v[188:191], v154 offset:1024
	ds_read_b128 v[192:195], v154 offset:2048
	ds_read_b128 v[196:199], v154 offset:3072
	ds_read_b128 v[200:203], v154 offset:4096
	ds_read_b128 v[208:211], v154 offset:5120
	ds_read_b128 v[212:215], v154 offset:6144
	ds_read_b128 v[216:219], v154 offset:7168
	global_load_lds_dwordx4 v[204:205], off
	v_lshl_add_u64 v[204:205], s[44:45], 0, v[142:143]
	s_add_i32 m0, s31, 0xe000
	s_nop 0
	global_load_lds_dwordx4 v[204:205], off
	s_waitcnt vmcnt(8)
	s_waitcnt lgkmcnt(0)
	s_barrier
; #define PG8_STAGE(bufoff, gbase, voff) do { _Pragma("unroll") for (int _i = 0; _i < 2; ++_i) \
;         __builtin_amdgcn_global_load_lds((const unsigned*)((const char*)(gbase) + (voff)[_i]), (PG8_LAS unsigned*)(lds + (bufoff) + ldsw + _i * 8192), 16, 0, 0); } while (0)
; #define PG8_LDA(dst, b, h) do { _Pragma("unroll") for (int m = 0; m < 4; ++m) _Pragma("unroll") for (int k = 0; k < 2; ++k) dst[m][k] = *(const PG8_LAS bf16x8*)(lds + PG8_SA(b, h) + aoff + m * 2048 + k * 1024); } while (0)
; #define PG8_MMA(ai, bj, At, Bt) do { __builtin_amdgcn_s_setprio(1); _Pragma("unroll") for (int m = 0; m < 4; ++m) _Pragma("unroll") for (int n = 0; n < 2; ++n) _Pragma("unroll") for (int k = 0; k < 2; ++k) \
;         acc[ai][bj][m][n] = __builtin_amdgcn_mfma_f32_16x16x32_bf16(Bt[n][k], At[m][k], acc[ai][bj][m][n], 0, 0, 0); __builtin_amdgcn_s_setprio(0); } while (0)
; #define PG8_WAIT_V(n) asm volatile("s_waitcnt vmcnt(" #n ")" ::: "memory")
; #define PG8_WAIT_L(n) asm volatile("s_waitcnt lgkmcnt(" #n ")" ::: "memory")
; #define PG8_BAR __builtin_amdgcn_s_barrier()
; #define PG8_SCHED __builtin_amdgcn_sched_barrier(0)
; template <class Epi, class Sched, bool ALIGN_EPI = false, bool SP2 = false>
; __device__ __forceinline__ void gemm_phase(PG8_LAS unsigned char* lds, const Gemm g, const Sched& S, const Epi& E) {
;     ...
;             PG8_WAIT_V(8); PG8_WAIT_L(0); PG8_BAR; PG8_MMA(0, 0, At, B0); PG8_MMA(0, 1, At, B1); PG8_BAR; PG8_SCHED;
;             PG8_LDA(At, 0, 1); PG8_STAGE(PG8_SB(0, 0), b2, voffB); PG8_STAGE(PG8_SB(0, 1), b2 + hstep, voffB); PG8_STAGE(PG8_SA(0, 0), a2, voffA);
;             PG8_WAIT_V(8); PG8_WAIT_L(0); PG8_BAR; PG8_MMA(1, 0, At, B0); PG8_MMA(1, 1, At, B1); PG8_BAR; PG8_SCHED;
	s_waitcnt lgkmcnt(0)
	v_mfma_f32_16x16x32_bf16 v[126:129], v[148:151], v[184:187], v[126:129]
	v_mfma_f32_16x16x32_bf16 v[122:125], v[160:163], v[184:187], v[122:125]
	v_mfma_f32_16x16x32_bf16 v[110:113], v[148:151], v[192:195], v[110:113]
	v_mfma_f32_16x16x32_bf16 v[106:109], v[160:163], v[192:195], v[106:109]
	v_mfma_f32_16x16x32_bf16 v[94:97], v[148:151], v[200:203], v[94:97]
	v_mfma_f32_16x16x32_bf16 v[90:93], v[160:163], v[200:203], v[90:93]
	v_mfma_f32_16x16x32_bf16 v[78:81], v[148:151], v[212:215], v[78:81]
	v_mfma_f32_16x16x32_bf16 v[74:77], v[160:163], v[212:215], v[74:77]
	v_mfma_f32_16x16x32_bf16 v[126:129], v[156:159], v[188:191], v[126:129]
	v_mfma_f32_16x16x32_bf16 v[122:125], v[164:167], v[188:191], v[122:125]
	v_mfma_f32_16x16x32_bf16 v[110:113], v[156:159], v[196:199], v[110:113]
	v_mfma_f32_16x16x32_bf16 v[106:109], v[164:167], v[196:199], v[106:109]
	v_mfma_f32_16x16x32_bf16 v[94:97], v[156:159], v[208:211], v[94:97]
	v_mfma_f32_16x16x32_bf16 v[90:93], v[164:167], v[208:211], v[90:93]
	v_mfma_f32_16x16x32_bf16 v[78:81], v[156:159], v[216:219], v[78:81]
	v_mfma_f32_16x16x32_bf16 v[74:77], v[164:167], v[216:219], v[74:77]
	v_mfma_f32_16x16x32_bf16 v[118:121], v[168:171], v[184:187], v[118:121]
	v_mfma_f32_16x16x32_bf16 v[114:117], v[176:179], v[184:187], v[114:117]
	v_mfma_f32_16x16x32_bf16 v[102:105], v[168:171], v[192:195], v[102:105]
	v_mfma_f32_16x16x32_bf16 v[98:101], v[176:179], v[192:195], v[98:101]
	v_mfma_f32_16x16x32_bf16 v[86:89], v[168:171], v[200:203], v[86:89]
	v_mfma_f32_16x16x32_bf16 v[82:85], v[176:179], v[200:203], v[82:85]
	v_mfma_f32_16x16x32_bf16 v[70:73], v[168:171], v[212:215], v[70:73]
	v_mfma_f32_16x16x32_bf16 v[66:69], v[176:179], v[212:215], v[66:69]
	v_mfma_f32_16x16x32_bf16 v[118:121], v[172:175], v[188:191], v[118:121]
	v_mfma_f32_16x16x32_bf16 v[114:117], v[180:183], v[188:191], v[114:117]
	v_mfma_f32_16x16x32_bf16 v[102:105], v[172:175], v[196:199], v[102:105]
	v_mfma_f32_16x16x32_bf16 v[98:101], v[180:183], v[196:199], v[98:101]
	v_mfma_f32_16x16x32_bf16 v[86:89], v[172:175], v[208:211], v[86:89]
	v_mfma_f32_16x16x32_bf16 v[82:85], v[180:183], v[208:211], v[82:85]
	v_mfma_f32_16x16x32_bf16 v[70:73], v[172:175], v[216:219], v[70:73]
	v_mfma_f32_16x16x32_bf16 v[66:69], v[180:183], v[216:219], v[66:69]
	s_barrier
	s_add_i32 s74, s68, s30
	s_mov_b32 m0, s74
	ds_read_b128 v[184:187], v154 offset:16384
	ds_read_b128 v[188:191], v154 offset:17408
	ds_read_b128 v[192:195], v154 offset:18432
	ds_read_b128 v[196:199], v154 offset:19456
	ds_read_b128 v[200:203], v154 offset:20480
	ds_read_b128 v[208:211], v154 offset:21504
	ds_read_b128 v[212:215], v154 offset:22528
	ds_read_b128 v[216:219], v154 offset:23552
	global_load_lds_dwordx4 v132, s[46:47]
	s_add_i32 m0, s74, 0x2000
	s_add_u32 s74, s46, 0x40000
	v_lshl_add_u64 v[220:221], s[46:47], 0, v[136:137]
	s_addc_u32 s75, s47, 0
	s_add_i32 s76, s69, s30
	global_load_lds_dwordx4 v136, s[46:47]
	s_mov_b32 m0, s76
	v_lshl_add_u64 v[224:225], s[48:49], 0, v[134:135]
	global_load_lds_dwordx4 v132, s[74:75]
	s_add_i32 m0, s76, 0x2000
	s_nop 0
	global_load_lds_dwordx4 v136, s[74:75]
	v_lshl_add_u64 v[222:223], s[48:49], 0, v[130:131]
	s_mov_b32 m0, s31
	s_nop 0
	global_load_lds_dwordx4 v130, s[48:49]
	s_mov_b32 m0, s50
	s_nop 0
	global_load_lds_dwordx4 v134, s[48:49]
	s_waitcnt vmcnt(8)
	s_waitcnt lgkmcnt(0)
	s_barrier
	s_waitcnt lgkmcnt(0)
	v_mfma_f32_16x16x32_bf16 v[62:65], v[148:151], v[184:187], v[62:65]
	v_mfma_f32_16x16x32_bf16 v[58:61], v[160:163], v[184:187], v[58:61]
	v_mfma_f32_16x16x32_bf16 v[46:49], v[148:151], v[192:195], v[46:49]
	v_mfma_f32_16x16x32_bf16 v[42:45], v[160:163], v[192:195], v[42:45]
	v_mfma_f32_16x16x32_bf16 v[30:33], v[148:151], v[200:203], v[30:33]
	v_mfma_f32_16x16x32_bf16 v[26:29], v[160:163], v[200:203], v[26:29]
	v_mfma_f32_16x16x32_bf16 v[14:17], v[148:151], v[212:215], v[14:17]
	v_mfma_f32_16x16x32_bf16 v[10:13], v[160:163], v[212:215], v[10:13]
	v_mfma_f32_16x16x32_bf16 v[62:65], v[156:159], v[188:191], v[62:65]
	v_mfma_f32_16x16x32_bf16 v[58:61], v[164:167], v[188:191], v[58:61]
	v_mfma_f32_16x16x32_bf16 v[46:49], v[156:159], v[196:199], v[46:49]
	v_mfma_f32_16x16x32_bf16 v[42:45], v[164:167], v[196:199], v[42:45]
	v_mfma_f32_16x16x32_bf16 v[30:33], v[156:159], v[208:211], v[30:33]
	v_mfma_f32_16x16x32_bf16 v[26:29], v[164:167], v[208:211], v[26:29]
	v_mfma_f32_16x16x32_bf16 v[14:17], v[156:159], v[216:219], v[14:17]
	v_mfma_f32_16x16x32_bf16 v[10:13], v[164:167], v[216:219], v[10:13]
	v_mfma_f32_16x16x32_bf16 v[54:57], v[168:171], v[184:187], v[54:57]
	v_mfma_f32_16x16x32_bf16 v[50:53], v[176:179], v[184:187], v[50:53]
	v_mfma_f32_16x16x32_bf16 v[38:41], v[168:171], v[192:195], v[38:41]
	v_mfma_f32_16x16x32_bf16 v[34:37], v[176:179], v[192:195], v[34:37]
	v_mfma_f32_16x16x32_bf16 v[22:25], v[168:171], v[200:203], v[22:25]
	v_mfma_f32_16x16x32_bf16 v[18:21], v[176:179], v[200:203], v[18:21]
	v_mfma_f32_16x16x32_bf16 v[6:9], v[168:171], v[212:215], v[6:9]
	v_mfma_f32_16x16x32_bf16 v[2:5], v[176:179], v[212:215], v[2:5]
	v_mfma_f32_16x16x32_bf16 v[54:57], v[172:175], v[188:191], v[54:57]
	v_mfma_f32_16x16x32_bf16 v[50:53], v[180:183], v[188:191], v[50:53]
	v_mfma_f32_16x16x32_bf16 v[38:41], v[172:175], v[196:199], v[38:41]
	v_mfma_f32_16x16x32_bf16 v[34:37], v[180:183], v[196:199], v[34:37]
	v_mfma_f32_16x16x32_bf16 v[22:25], v[172:175], v[208:211], v[22:25]
	v_mfma_f32_16x16x32_bf16 v[18:21], v[180:183], v[208:211], v[18:21]
	v_mfma_f32_16x16x32_bf16 v[6:9], v[172:175], v[216:219], v[6:9]
	v_mfma_f32_16x16x32_bf16 v[2:5], v[180:183], v[216:219], v[2:5]
	s_barrier
; #define PG8_STAGE(bufoff, gbase, voff) do { _Pragma("unroll") for (int _i = 0; _i < 2; ++_i) \
;         __builtin_amdgcn_global_load_lds((const unsigned*)((const char*)(gbase) + (voff)[_i]), (PG8_LAS unsigned*)(lds + (bufoff) + ldsw + _i * 8192), 16, 0, 0); } while (0)
; #define PG8_LDA(dst, b, h) do { _Pragma("unroll") for (int m = 0; m < 4; ++m) _Pragma("unroll") for (int k = 0; k < 2; ++k) dst[m][k] = *(const PG8_LAS bf16x8*)(lds + PG8_SA(b, h) + aoff + m * 2048 + k * 1024); } while (0)
; #define PG8_LDB(dst, b, h) do { _Pragma("unroll") for (int n = 0; n < 2; ++n) _Pragma("unroll") for (int k = 0; k < 2; ++k) dst[n][k] = *(const PG8_LAS bf16x8*)(lds + PG8_SB(b, h) + boff + n * 2048 + k * 1024); } while (0)
; #define PG8_MMA(ai, bj, At, Bt) do { __builtin_amdgcn_s_setprio(1); _Pragma("unroll") for (int m = 0; m < 4; ++m) _Pragma("unroll") for (int n = 0; n < 2; ++n) _Pragma("unroll") for (int k = 0; k < 2; ++k) \
;         acc[ai][bj][m][n] = __builtin_amdgcn_mfma_f32_16x16x32_bf16(Bt[n][k], At[m][k], acc[ai][bj][m][n], 0, 0, 0); __builtin_amdgcn_s_setprio(0); } while (0)
; #define PG8_WAIT_V(n) asm volatile("s_waitcnt vmcnt(" #n ")" ::: "memory")
; #define PG8_WAIT_L(n) asm volatile("s_waitcnt lgkmcnt(" #n ")" ::: "memory")
; #define PG8_BAR __builtin_amdgcn_s_barrier()
; #define PG8_SCHED __builtin_amdgcn_sched_barrier(0)
; template <class Epi, class Sched, bool ALIGN_EPI = false, bool SP2 = false>
; __device__ __forceinline__ void gemm_phase(PG8_LAS unsigned char* lds, const Gemm g, const Sched& S, const Epi& E) {
;     ...
;             PG8_LDB(B0, 1, 0); PG8_LDB(B1, 1, 1); PG8_SCHED; PG8_LDA(At, 1, 0); PG8_STAGE(PG8_SA(0, 1), a2 + hstep, voffA);
;             PG8_WAIT_V(8); PG8_WAIT_L(0); PG8_BAR; PG8_MMA(0, 0, At, B0); PG8_MMA(0, 1, At, B1); PG8_BAR; PG8_SCHED;
;             PG8_LDA(At, 1, 1); PG8_STAGE(PG8_SB(1, 0), b3, voffB); PG8_STAGE(PG8_SB(1, 1), b3 + hstep, voffB); PG8_STAGE(PG8_SA(1, 0), a3, voffA);
;             PG8_WAIT_V(8); PG8_WAIT_L(0); PG8_BAR; PG8_MMA(1, 0, At, B0); PG8_MMA(1, 1, At, B1); PG8_BAR; PG8_SCHED;
	s_add_i32 s74, 0, 0x18000
	s_add_i32 s75, 0, 0x1c000
	v_add_u32_e32 v164, s74, v139
	v_add_u32_e32 v180, s75, v139
	ds_read_b128 v[148:151], v164
	ds_read_b128 v[156:159], v164 offset:1024
	ds_read_b128 v[160:163], v164 offset:2048
	ds_read_b128 v[164:167], v164 offset:3072
	ds_read_b128 v[168:171], v180
	ds_read_b128 v[172:175], v180 offset:1024
	ds_read_b128 v[176:179], v180 offset:2048
	ds_read_b128 v[180:183], v180 offset:3072
	s_add_u32 s48, s48, 0x40000
	s_addc_u32 s49, s49, 0
	s_mov_b32 m0, s51
	ds_read_b128 v[184:187], v154 offset:32768
	ds_read_b128 v[188:191], v154 offset:33792
	ds_read_b128 v[192:195], v154 offset:34816
	ds_read_b128 v[196:199], v154 offset:35840
	ds_read_b128 v[200:203], v154 offset:36864
	ds_read_b128 v[208:211], v154 offset:37888
	ds_read_b128 v[212:215], v154 offset:38912
	ds_read_b128 v[216:219], v154 offset:39936
	global_load_lds_dwordx4 v130, s[48:49]
	s_mov_b32 m0, s60
	s_nop 0
	global_load_lds_dwordx4 v134, s[48:49]
	s_waitcnt vmcnt(8)
	s_waitcnt lgkmcnt(0)
	s_barrier
	s_waitcnt lgkmcnt(0)
	v_mfma_f32_16x16x32_bf16 v[126:129], v[148:151], v[184:187], v[126:129]
	v_mfma_f32_16x16x32_bf16 v[122:125], v[160:163], v[184:187], v[122:125]
	v_mfma_f32_16x16x32_bf16 v[110:113], v[148:151], v[192:195], v[110:113]
	v_mfma_f32_16x16x32_bf16 v[106:109], v[160:163], v[192:195], v[106:109]
	v_mfma_f32_16x16x32_bf16 v[94:97], v[148:151], v[200:203], v[94:97]
	v_mfma_f32_16x16x32_bf16 v[90:93], v[160:163], v[200:203], v[90:93]
	v_mfma_f32_16x16x32_bf16 v[78:81], v[148:151], v[212:215], v[78:81]
	v_mfma_f32_16x16x32_bf16 v[74:77], v[160:163], v[212:215], v[74:77]
	v_mfma_f32_16x16x32_bf16 v[126:129], v[156:159], v[188:191], v[126:129]
	v_mfma_f32_16x16x32_bf16 v[122:125], v[164:167], v[188:191], v[122:125]
	v_mfma_f32_16x16x32_bf16 v[110:113], v[156:159], v[196:199], v[110:113]
	v_mfma_f32_16x16x32_bf16 v[106:109], v[164:167], v[196:199], v[106:109]
	v_mfma_f32_16x16x32_bf16 v[94:97], v[156:159], v[208:211], v[94:97]
	v_mfma_f32_16x16x32_bf16 v[90:93], v[164:167], v[208:211], v[90:93]
	v_mfma_f32_16x16x32_bf16 v[78:81], v[156:159], v[216:219], v[78:81]
	v_mfma_f32_16x16x32_bf16 v[74:77], v[164:167], v[216:219], v[74:77]
	v_mfma_f32_16x16x32_bf16 v[118:121], v[168:171], v[184:187], v[118:121]
	v_mfma_f32_16x16x32_bf16 v[114:117], v[176:179], v[184:187], v[114:117]
	v_mfma_f32_16x16x32_bf16 v[102:105], v[168:171], v[192:195], v[102:105]
	v_mfma_f32_16x16x32_bf16 v[98:101], v[176:179], v[192:195], v[98:101]
	v_mfma_f32_16x16x32_bf16 v[86:89], v[168:171], v[200:203], v[86:89]
	v_mfma_f32_16x16x32_bf16 v[82:85], v[176:179], v[200:203], v[82:85]
	v_mfma_f32_16x16x32_bf16 v[70:73], v[168:171], v[212:215], v[70:73]
	v_mfma_f32_16x16x32_bf16 v[66:69], v[176:179], v[212:215], v[66:69]
	v_mfma_f32_16x16x32_bf16 v[118:121], v[172:175], v[188:191], v[118:121]
	v_mfma_f32_16x16x32_bf16 v[114:117], v[180:183], v[188:191], v[114:117]
	v_mfma_f32_16x16x32_bf16 v[102:105], v[172:175], v[196:199], v[102:105]
	v_mfma_f32_16x16x32_bf16 v[98:101], v[180:183], v[196:199], v[98:101]
	v_mfma_f32_16x16x32_bf16 v[86:89], v[172:175], v[208:211], v[86:89]
	v_mfma_f32_16x16x32_bf16 v[82:85], v[180:183], v[208:211], v[82:85]
	v_mfma_f32_16x16x32_bf16 v[70:73], v[172:175], v[216:219], v[70:73]
	v_mfma_f32_16x16x32_bf16 v[66:69], v[180:183], v[216:219], v[66:69]
	s_barrier
	s_add_i32 s48, s74, s30
	s_mov_b32 m0, s48
	ds_read_b128 v[184:187], v154 offset:49152
	ds_read_b128 v[188:191], v154 offset:50176
	ds_read_b128 v[192:195], v154 offset:51200
	ds_read_b128 v[196:199], v154 offset:52224
	ds_read_b128 v[200:203], v154 offset:53248
	ds_read_b128 v[208:211], v154 offset:54272
	ds_read_b128 v[212:215], v154 offset:55296
	ds_read_b128 v[216:219], v154 offset:56320
	s_add_u32 s98, s46, s14
	s_addc_u32 s99, s47, s15
	global_load_lds_dwordx4 v132, s[98:99]
	s_add_i32 m0, s48, 0x2000
	s_add_u32 s46, s46, 0x40080
	v_lshl_add_u64 v[204:205], v[220:221], 0, s[14:15]
	s_addc_u32 s47, s47, 0
	s_add_i32 s48, s75, s30
	global_load_lds_dwordx4 v[204:205], off
	s_mov_b32 m0, s48
	s_nop 0
	global_load_lds_dwordx4 v132, s[46:47]
	s_add_i32 m0, s48, 0x2000
	s_nop 0
	global_load_lds_dwordx4 v136, s[46:47]
	v_lshl_add_u64 v[204:205], v[222:223], 0, s[14:15]
	s_mov_b32 m0, s62
	s_nop 0
	global_load_lds_dwordx4 v[204:205], off
	v_lshl_add_u64 v[204:205], v[224:225], 0, s[14:15]
	s_mov_b32 m0, s63
	s_nop 0
	global_load_lds_dwordx4 v[204:205], off
	s_waitcnt vmcnt(8)
	s_waitcnt lgkmcnt(0)
	s_barrier
	s_waitcnt lgkmcnt(0)
	v_mfma_f32_16x16x32_bf16 v[62:65], v[148:151], v[184:187], v[62:65]
	v_mfma_f32_16x16x32_bf16 v[58:61], v[160:163], v[184:187], v[58:61]
	v_mfma_f32_16x16x32_bf16 v[46:49], v[148:151], v[192:195], v[46:49]
	v_mfma_f32_16x16x32_bf16 v[42:45], v[160:163], v[192:195], v[42:45]
	v_mfma_f32_16x16x32_bf16 v[30:33], v[148:151], v[200:203], v[30:33]
	v_mfma_f32_16x16x32_bf16 v[26:29], v[160:163], v[200:203], v[26:29]
	v_mfma_f32_16x16x32_bf16 v[14:17], v[148:151], v[212:215], v[14:17]
	v_mfma_f32_16x16x32_bf16 v[10:13], v[160:163], v[212:215], v[10:13]
	v_mfma_f32_16x16x32_bf16 v[62:65], v[156:159], v[188:191], v[62:65]
	v_mfma_f32_16x16x32_bf16 v[58:61], v[164:167], v[188:191], v[58:61]
	v_mfma_f32_16x16x32_bf16 v[46:49], v[156:159], v[196:199], v[46:49]
	v_mfma_f32_16x16x32_bf16 v[42:45], v[164:167], v[196:199], v[42:45]
	v_mfma_f32_16x16x32_bf16 v[30:33], v[156:159], v[208:211], v[30:33]
	v_mfma_f32_16x16x32_bf16 v[26:29], v[164:167], v[208:211], v[26:29]
	v_mfma_f32_16x16x32_bf16 v[14:17], v[156:159], v[216:219], v[14:17]
	v_mfma_f32_16x16x32_bf16 v[10:13], v[164:167], v[216:219], v[10:13]
	v_mfma_f32_16x16x32_bf16 v[54:57], v[168:171], v[184:187], v[54:57]
	v_mfma_f32_16x16x32_bf16 v[50:53], v[176:179], v[184:187], v[50:53]
	v_mfma_f32_16x16x32_bf16 v[38:41], v[168:171], v[192:195], v[38:41]
	v_mfma_f32_16x16x32_bf16 v[34:37], v[176:179], v[192:195], v[34:37]
	v_mfma_f32_16x16x32_bf16 v[22:25], v[168:171], v[200:203], v[22:25]
	v_mfma_f32_16x16x32_bf16 v[18:21], v[176:179], v[200:203], v[18:21]
	v_mfma_f32_16x16x32_bf16 v[6:9], v[168:171], v[212:215], v[6:9]
	v_mfma_f32_16x16x32_bf16 v[2:5], v[176:179], v[212:215], v[2:5]
	v_mfma_f32_16x16x32_bf16 v[54:57], v[172:175], v[188:191], v[54:57]
	v_mfma_f32_16x16x32_bf16 v[50:53], v[180:183], v[188:191], v[50:53]
	v_mfma_f32_16x16x32_bf16 v[38:41], v[172:175], v[196:199], v[38:41]
	v_mfma_f32_16x16x32_bf16 v[34:37], v[180:183], v[196:199], v[34:37]
	v_mfma_f32_16x16x32_bf16 v[22:25], v[172:175], v[208:211], v[22:25]
	v_mfma_f32_16x16x32_bf16 v[18:21], v[180:183], v[208:211], v[18:21]
	v_mfma_f32_16x16x32_bf16 v[6:9], v[172:175], v[216:219], v[6:9]
	v_mfma_f32_16x16x32_bf16 v[2:5], v[180:183], v[216:219], v[2:5]
	s_add_i32 s73, s73, 2
	s_add_u32 s44, s44, 0x100
	s_addc_u32 s45, s45, 0
	s_add_u32 s71, s71, 0x100
	s_addc_u32 s72, s72, 0
	s_cmp_gt_u32 s73, 13
	s_barrier
	s_cbranch_scc0 .LBB0_646
	s_setprio 0
	s_and_b64 vcc, exec, s[16:17]
	s_cbranch_vccz .LBB0_649
	s_barrier

; #define PG8_STAGE(bufoff, gbase, voff) do { _Pragma("unroll") for (int _i = 0; _i < 2; ++_i) \
;         __builtin_amdgcn_global_load_lds((const unsigned*)((const char*)(gbase) + (voff)[_i]), (PG8_LAS unsigned*)(lds + (bufoff) + ldsw + _i * 8192), 16, 0, 0); } while (0)
; #define PG8_LDA(dst, b, h) do { _Pragma("unroll") for (int m = 0; m < 4; ++m) _Pragma("unroll") for (int k = 0; k < 2; ++k) dst[m][k] = *(const PG8_LAS bf16x8*)(lds + PG8_SA(b, h) + aoff + m * 2048 + k * 1024); } while (0)
; #define PG8_LDB(dst, b, h) do { _Pragma("unroll") for (int n = 0; n < 2; ++n) _Pragma("unroll") for (int k = 0; k < 2; ++k) dst[n][k] = *(const PG8_LAS bf16x8*)(lds + PG8_SB(b, h) + boff + n * 2048 + k * 1024); } while (0)
; #define PG8_SCHED __builtin_amdgcn_sched_barrier(0)
; template <class Epi, class Sched, bool ALIGN_EPI = false, bool SP2 = false>
; __device__ __forceinline__ void gemm_phase(PG8_LAS unsigned char* lds, const Gemm g, const Sched& S, const Epi& E) {
;     ...
;         const bool has_next = S.next(ui + 1, nxt);
;         const char* nA = has_next ? (const char*)g.A + (size_t)nxt.pm * tstep : cA; const char* nB = has_next ? (const char*)g.Bt + (size_t)nxt.pn * tstep : cB;
;         for (int t = 0; t < nt; t += 2) {
;             const bool last = (t == nt - 2);
;             const char* a1 = cA + (size_t)(t + 1) * kstep;
;             const char* a2 = last ? nA : cA + (size_t)(t + 2) * kstep; const char* b2 = last ? nB : cB + (size_t)(t + 2) * kstep;
;             const char* a3 = a2 + kstep; const char* b3 = b2 + kstep;
;             if (last && has_next) S.a_ready(nxt);
;             if constexpr (SP2) {
;             PG8_LDB(B0, 0, 0); PG8_LDB(B1, 0, 1); PG8_SCHED; PG8_LDA(At, 0, 0); PG8_STAGE(PG8_SA(1, 1), a1 + hstep, voffA);
.LBB0_739:
	s_ashr_i32 s19, s18, 31
	s_lshl_b64 s[20:21], s[18:19], 19
	s_add_u32 s20, s42, s20
	s_addc_u32 s21, s43, s21
	s_and_b64 s[22:23], s[0:1], exec
	s_cselect_b32 s19, s21, s31
	s_cselect_b32 s25, s20, s30
	s_ashr_i32 s17, s16, 31
	s_lshl_b64 s[22:23], s[16:17], 19
	s_add_u32 s22, s38, s22
	s_addc_u32 s23, s39, s23
	s_and_b64 s[44:45], s[0:1], exec
	s_cselect_b32 s17, s23, s41
	s_cselect_b32 s27, s22, s40
	s_add_u32 s30, s30, 0x40080
	s_addc_u32 s31, s31, 0
	s_add_u32 s33, s40, 0x100
	s_addc_u32 s70, s41, 0
	s_mov_b32 s71, -2
	s_bitcmp1_b32 s14, 0
	s_cbranch_scc1 .Lnp_740
	s_setprio 1
.Lnp_740:
	ds_read_b128 v[156:159], v152
	ds_read_b128 v[160:163], v152 offset:1024
	ds_read_b128 v[164:167], v152 offset:2048
	ds_read_b128 v[168:171], v152 offset:3072
	ds_read_b128 v[172:175], v153
	ds_read_b128 v[176:179], v153 offset:1024
	ds_read_b128 v[180:183], v153 offset:2048
	ds_read_b128 v[184:187], v153 offset:3072
	s_add_u32 s40, s30, 0xfffc0080
	s_addc_u32 s41, s31, -1
	s_cmp_eq_u32 s71, 12
	s_cselect_b32 s45, s19, s41
	s_cselect_b32 s44, s25, s40
	s_cselect_b32 s41, s17, s70
	s_cselect_b32 s40, s27, s33
	v_lshl_add_u64 v[148:149], s[30:31], 0, v[140:141]
	s_add_i32 m0, s48, 0xc000
	ds_read_b128 v[188:191], v154
	ds_read_b128 v[192:195], v154 offset:1024
	ds_read_b128 v[196:199], v154 offset:2048
	ds_read_b128 v[200:203], v154 offset:3072
	ds_read_b128 v[208:211], v154 offset:4096
	ds_read_b128 v[212:215], v154 offset:5120
	ds_read_b128 v[216:219], v154 offset:6144
	ds_read_b128 v[220:223], v154 offset:7168
	global_load_lds_dwordx4 v[148:149], off
	v_lshl_add_u64 v[148:149], s[30:31], 0, v[142:143]
	s_add_i32 m0, s48, 0xe000
	s_nop 0
	global_load_lds_dwordx4 v[148:149], off
	s_waitcnt vmcnt(16)
	s_cmp_gt_u32 s69, 1
	s_cbranch_scc1 .Lpw_740_0
	s_waitcnt vmcnt(8)

; #define PG8_STAGE(bufoff, gbase, voff) do { _Pragma("unroll") for (int _i = 0; _i < 2; ++_i) \
;         __builtin_amdgcn_global_load_lds((const unsigned*)((const char*)(gbase) + (voff)[_i]), (PG8_LAS unsigned*)(lds + (bufoff) + ldsw + _i * 8192), 16, 0, 0); } while (0)
; #define PG8_LDA(dst, b, h) do { _Pragma("unroll") for (int m = 0; m < 4; ++m) _Pragma("unroll") for (int k = 0; k < 2; ++k) dst[m][k] = *(const PG8_LAS bf16x8*)(lds + PG8_SA(b, h) + aoff + m * 2048 + k * 1024); } while (0)
; #define PG8_LDB(dst, b, h) do { _Pragma("unroll") for (int n = 0; n < 2; ++n) _Pragma("unroll") for (int k = 0; k < 2; ++k) dst[n][k] = *(const PG8_LAS bf16x8*)(lds + PG8_SB(b, h) + boff + n * 2048 + k * 1024); } while (0)
; #define PG8_MMA(ai, bj, At, Bt) do { __builtin_amdgcn_s_setprio(1); _Pragma("unroll") for (int m = 0; m < 4; ++m) _Pragma("unroll") for (int n = 0; n < 2; ++n) _Pragma("unroll") for (int k = 0; k < 2; ++k) \
;         acc[ai][bj][m][n] = __builtin_amdgcn_mfma_f32_16x16x32_bf16(Bt[n][k], At[m][k], acc[ai][bj][m][n], 0, 0, 0); __builtin_amdgcn_s_setprio(0); } while (0)
; #define PG8_WAIT_V(n) asm volatile("s_waitcnt vmcnt(" #n ")" ::: "memory")
; #define PG8_WAIT_L(n) asm volatile("s_waitcnt lgkmcnt(" #n ")" ::: "memory")
; #define PG8_BAR __builtin_amdgcn_s_barrier()
; #define PG8_SCHED __builtin_amdgcn_sched_barrier(0)
; template <class Epi, class Sched, bool ALIGN_EPI = false, bool SP2 = false>
; __device__ __forceinline__ void gemm_phase(PG8_LAS unsigned char* lds, const Gemm g, const Sched& S, const Epi& E) {
;     ...
;             PG8_LDB(B0, 0, 0); PG8_LDB(B1, 0, 1); PG8_SCHED; PG8_LDA(At, 0, 0); PG8_STAGE(PG8_SA(1, 1), a1 + hstep, voffA);
;             PG8_WAIT_V(8); PG8_WAIT_L(0); PG8_BAR; PG8_MMA(0, 0, At, B0); PG8_MMA(0, 1, At, B1); PG8_BAR; PG8_SCHED;
;             PG8_LDA(At, 0, 1); PG8_STAGE(PG8_SB(0, 0), b2, voffB); PG8_STAGE(PG8_SB(0, 1), b2 + hstep, voffB); PG8_STAGE(PG8_SA(0, 0), a2, voffA);
;             PG8_WAIT_V(8); PG8_WAIT_L(0); PG8_BAR; PG8_MMA(1, 0, At, B0); PG8_MMA(1, 1, At, B1); PG8_BAR; PG8_SCHED;
.LBB0_740:
	ds_read_b128 v[156:159], v152
	ds_read_b128 v[160:163], v152 offset:1024
	ds_read_b128 v[164:167], v152 offset:2048
	ds_read_b128 v[168:171], v152 offset:3072
	ds_read_b128 v[172:175], v153
	ds_read_b128 v[176:179], v153 offset:1024
	ds_read_b128 v[180:183], v153 offset:2048
	ds_read_b128 v[184:187], v153 offset:3072
	s_add_u32 s40, s30, 0xfffc0080
	s_addc_u32 s41, s31, -1
	s_cmp_eq_u32 s71, 12
	s_cselect_b32 s45, s19, s41
	s_cselect_b32 s44, s25, s40
	s_cselect_b32 s41, s17, s70
	s_cselect_b32 s40, s27, s33
	v_lshl_add_u64 v[148:149], s[30:31], 0, v[140:141]
	s_add_i32 m0, s48, 0xc000
	ds_read_b128 v[188:191], v154
	ds_read_b128 v[192:195], v154 offset:1024
	ds_read_b128 v[196:199], v154 offset:2048
	ds_read_b128 v[200:203], v154 offset:3072
	ds_read_b128 v[208:211], v154 offset:4096
	ds_read_b128 v[212:215], v154 offset:5120
	ds_read_b128 v[216:219], v154 offset:6144
	ds_read_b128 v[220:223], v154 offset:7168
	global_load_lds_dwordx4 v[148:149], off
	v_lshl_add_u64 v[148:149], s[30:31], 0, v[142:143]
	s_add_i32 m0, s48, 0xe000
	s_nop 0
	global_load_lds_dwordx4 v[148:149], off
	s_waitcnt vmcnt(8)
	s_waitcnt lgkmcnt(0)
	s_barrier
	s_waitcnt lgkmcnt(0)
	v_mfma_f32_16x16x32_bf16 v[126:129], v[156:159], v[188:191], v[126:129]
	v_mfma_f32_16x16x32_bf16 v[122:125], v[164:167], v[188:191], v[122:125]
	v_mfma_f32_16x16x32_bf16 v[110:113], v[156:159], v[196:199], v[110:113]
	v_mfma_f32_16x16x32_bf16 v[106:109], v[164:167], v[196:199], v[106:109]
	v_mfma_f32_16x16x32_bf16 v[94:97], v[156:159], v[208:211], v[94:97]
	v_mfma_f32_16x16x32_bf16 v[90:93], v[164:167], v[208:211], v[90:93]
	v_mfma_f32_16x16x32_bf16 v[78:81], v[156:159], v[216:219], v[78:81]
	v_mfma_f32_16x16x32_bf16 v[74:77], v[164:167], v[216:219], v[74:77]
	v_mfma_f32_16x16x32_bf16 v[126:129], v[160:163], v[192:195], v[126:129]
	v_mfma_f32_16x16x32_bf16 v[122:125], v[168:171], v[192:195], v[122:125]
	v_mfma_f32_16x16x32_bf16 v[110:113], v[160:163], v[200:203], v[110:113]
	v_mfma_f32_16x16x32_bf16 v[106:109], v[168:171], v[200:203], v[106:109]
	v_mfma_f32_16x16x32_bf16 v[94:97], v[160:163], v[212:215], v[94:97]
	v_mfma_f32_16x16x32_bf16 v[90:93], v[168:171], v[212:215], v[90:93]
	v_mfma_f32_16x16x32_bf16 v[78:81], v[160:163], v[220:223], v[78:81]
	v_mfma_f32_16x16x32_bf16 v[74:77], v[168:171], v[220:223], v[74:77]
	v_mfma_f32_16x16x32_bf16 v[118:121], v[172:175], v[188:191], v[118:121]
	v_mfma_f32_16x16x32_bf16 v[114:117], v[180:183], v[188:191], v[114:117]
	v_mfma_f32_16x16x32_bf16 v[102:105], v[172:175], v[196:199], v[102:105]
	v_mfma_f32_16x16x32_bf16 v[98:101], v[180:183], v[196:199], v[98:101]
	v_mfma_f32_16x16x32_bf16 v[86:89], v[172:175], v[208:211], v[86:89]
	v_mfma_f32_16x16x32_bf16 v[82:85], v[180:183], v[208:211], v[82:85]
	v_mfma_f32_16x16x32_bf16 v[70:73], v[172:175], v[216:219], v[70:73]
	v_mfma_f32_16x16x32_bf16 v[66:69], v[180:183], v[216:219], v[66:69]
	v_mfma_f32_16x16x32_bf16 v[118:121], v[176:179], v[192:195], v[118:121]
	v_mfma_f32_16x16x32_bf16 v[114:117], v[184:187], v[192:195], v[114:117]
	v_mfma_f32_16x16x32_bf16 v[102:105], v[176:179], v[200:203], v[102:105]
	v_mfma_f32_16x16x32_bf16 v[98:101], v[184:187], v[200:203], v[98:101]
	v_mfma_f32_16x16x32_bf16 v[86:89], v[176:179], v[212:215], v[86:89]
	v_mfma_f32_16x16x32_bf16 v[82:85], v[184:187], v[212:215], v[82:85]
	v_mfma_f32_16x16x32_bf16 v[70:73], v[176:179], v[220:223], v[70:73]
	v_mfma_f32_16x16x32_bf16 v[66:69], v[184:187], v[220:223], v[66:69]
	s_barrier
	s_add_i32 s72, s66, s47
	s_mov_b32 m0, s72
	ds_read_b128 v[188:191], v154 offset:16384
	ds_read_b128 v[192:195], v154 offset:17408
	ds_read_b128 v[196:199], v154 offset:18432
	ds_read_b128 v[200:203], v154 offset:19456
	ds_read_b128 v[208:211], v154 offset:20480
	ds_read_b128 v[212:215], v154 offset:21504
	ds_read_b128 v[216:219], v154 offset:22528
	ds_read_b128 v[220:223], v154 offset:23552
	global_load_lds_dwordx4 v132, s[40:41]
	s_add_i32 m0, s72, 0x2000
	s_add_u32 s72, s40, 0x40000
	v_lshl_add_u64 v[204:205], s[40:41], 0, v[136:137]
	s_addc_u32 s73, s41, 0
	s_add_i32 s74, s67, s47
	global_load_lds_dwordx4 v136, s[40:41]
	s_mov_b32 m0, s74
	v_lshl_add_u64 v[226:227], s[44:45], 0, v[134:135]
	global_load_lds_dwordx4 v132, s[72:73]
	s_add_i32 m0, s74, 0x2000
	s_nop 0
	global_load_lds_dwordx4 v136, s[72:73]
	v_lshl_add_u64 v[224:225], s[44:45], 0, v[130:131]
	s_mov_b32 m0, s48
	s_nop 0
	global_load_lds_dwordx4 v130, s[44:45]
	s_mov_b32 m0, s49
	s_nop 0
	global_load_lds_dwordx4 v134, s[44:45]
	s_waitcnt vmcnt(8)
	s_waitcnt lgkmcnt(0)
	s_barrier
	s_waitcnt lgkmcnt(0)
	v_mfma_f32_16x16x32_bf16 v[62:65], v[156:159], v[188:191], v[62:65]
	v_mfma_f32_16x16x32_bf16 v[58:61], v[164:167], v[188:191], v[58:61]
	v_mfma_f32_16x16x32_bf16 v[46:49], v[156:159], v[196:199], v[46:49]
	v_mfma_f32_16x16x32_bf16 v[42:45], v[164:167], v[196:199], v[42:45]
	v_mfma_f32_16x16x32_bf16 v[30:33], v[156:159], v[208:211], v[30:33]
	v_mfma_f32_16x16x32_bf16 v[26:29], v[164:167], v[208:211], v[26:29]
	v_mfma_f32_16x16x32_bf16 v[14:17], v[156:159], v[216:219], v[14:17]
	v_mfma_f32_16x16x32_bf16 v[10:13], v[164:167], v[216:219], v[10:13]
	v_mfma_f32_16x16x32_bf16 v[62:65], v[160:163], v[192:195], v[62:65]
	v_mfma_f32_16x16x32_bf16 v[58:61], v[168:171], v[192:195], v[58:61]
	v_mfma_f32_16x16x32_bf16 v[46:49], v[160:163], v[200:203], v[46:49]
	v_mfma_f32_16x16x32_bf16 v[42:45], v[168:171], v[200:203], v[42:45]
	v_mfma_f32_16x16x32_bf16 v[30:33], v[160:163], v[212:215], v[30:33]
	v_mfma_f32_16x16x32_bf16 v[26:29], v[168:171], v[212:215], v[26:29]
	v_mfma_f32_16x16x32_bf16 v[14:17], v[160:163], v[220:223], v[14:17]
	v_mfma_f32_16x16x32_bf16 v[10:13], v[168:171], v[220:223], v[10:13]
	v_mfma_f32_16x16x32_bf16 v[54:57], v[172:175], v[188:191], v[54:57]
	v_mfma_f32_16x16x32_bf16 v[50:53], v[180:183], v[188:191], v[50:53]
	v_mfma_f32_16x16x32_bf16 v[38:41], v[172:175], v[196:199], v[38:41]
	v_mfma_f32_16x16x32_bf16 v[34:37], v[180:183], v[196:199], v[34:37]
	v_mfma_f32_16x16x32_bf16 v[22:25], v[172:175], v[208:211], v[22:25]
	v_mfma_f32_16x16x32_bf16 v[18:21], v[180:183], v[208:211], v[18:21]
	v_mfma_f32_16x16x32_bf16 v[6:9], v[172:175], v[216:219], v[6:9]
	v_mfma_f32_16x16x32_bf16 v[2:5], v[180:183], v[216:219], v[2:5]
	v_mfma_f32_16x16x32_bf16 v[54:57], v[176:179], v[192:195], v[54:57]
	v_mfma_f32_16x16x32_bf16 v[50:53], v[184:187], v[192:195], v[50:53]
	v_mfma_f32_16x16x32_bf16 v[38:41], v[176:179], v[200:203], v[38:41]
	v_mfma_f32_16x16x32_bf16 v[34:37], v[184:187], v[200:203], v[34:37]
	v_mfma_f32_16x16x32_bf16 v[22:25], v[176:179], v[212:215], v[22:25]
	v_mfma_f32_16x16x32_bf16 v[18:21], v[184:187], v[212:215], v[18:21]
	v_mfma_f32_16x16x32_bf16 v[6:9], v[176:179], v[220:223], v[6:9]
	v_mfma_f32_16x16x32_bf16 v[2:5], v[184:187], v[220:223], v[2:5]
	s_barrier
; #define PG8_STAGE(bufoff, gbase, voff) do { _Pragma("unroll") for (int _i = 0; _i < 2; ++_i) \
;         __builtin_amdgcn_global_load_lds((const unsigned*)((const char*)(gbase) + (voff)[_i]), (PG8_LAS unsigned*)(lds + (bufoff) + ldsw + _i * 8192), 16, 0, 0); } while (0)
; #define PG8_LDA(dst, b, h) do { _Pragma("unroll") for (int m = 0; m < 4; ++m) _Pragma("unroll") for (int k = 0; k < 2; ++k) dst[m][k] = *(const PG8_LAS bf16x8*)(lds + PG8_SA(b, h) + aoff + m * 2048 + k * 1024); } while (0)
; #define PG8_LDB(dst, b, h) do { _Pragma("unroll") for (int n = 0; n < 2; ++n) _Pragma("unroll") for (int k = 0; k < 2; ++k) dst[n][k] = *(const PG8_LAS bf16x8*)(lds + PG8_SB(b, h) + boff + n * 2048 + k * 1024); } while (0)
; #define PG8_MMA(ai, bj, At, Bt) do { __builtin_amdgcn_s_setprio(1); _Pragma("unroll") for (int m = 0; m < 4; ++m) _Pragma("unroll") for (int n = 0; n < 2; ++n) _Pragma("unroll") for (int k = 0; k < 2; ++k) \
;         acc[ai][bj][m][n] = __builtin_amdgcn_mfma_f32_16x16x32_bf16(Bt[n][k], At[m][k], acc[ai][bj][m][n], 0, 0, 0); __builtin_amdgcn_s_setprio(0); } while (0)
; #define PG8_WAIT_V(n) asm volatile("s_waitcnt vmcnt(" #n ")" ::: "memory")
; #define PG8_WAIT_L(n) asm volatile("s_waitcnt lgkmcnt(" #n ")" ::: "memory")
; #define PG8_BAR __builtin_amdgcn_s_barrier()
; #define PG8_SCHED __builtin_amdgcn_sched_barrier(0)
; template <class Epi, class Sched, bool ALIGN_EPI = false, bool SP2 = false>
; __device__ __forceinline__ void gemm_phase(PG8_LAS unsigned char* lds, const Gemm g, const Sched& S, const Epi& E) {
;     ...
;             PG8_LDB(B0, 1, 0); PG8_LDB(B1, 1, 1); PG8_SCHED; PG8_LDA(At, 1, 0); PG8_STAGE(PG8_SA(0, 1), a2 + hstep, voffA);
;             PG8_WAIT_V(8); PG8_WAIT_L(0); PG8_BAR; PG8_MMA(0, 0, At, B0); PG8_MMA(0, 1, At, B1); PG8_BAR; PG8_SCHED;
;             PG8_LDA(At, 1, 1); PG8_STAGE(PG8_SB(1, 0), b3, voffB); PG8_STAGE(PG8_SB(1, 1), b3 + hstep, voffB); PG8_STAGE(PG8_SA(1, 0), a3, voffA);
;             PG8_WAIT_V(8); PG8_WAIT_L(0); PG8_BAR; PG8_MMA(1, 0, At, B0); PG8_MMA(1, 1, At, B1); PG8_BAR; PG8_SCHED;
	s_add_i32 s72, 0, 0x18000
	v_add_u32_e32 v150, s72, v151
	s_add_i32 s73, 0, 0x1c000
	ds_read_b128 v[156:159], v150
	ds_read_b128 v[160:163], v150 offset:1024
	ds_read_b128 v[164:167], v150 offset:2048
	ds_read_b128 v[168:171], v150 offset:3072
	v_add_u32_e32 v150, s73, v151
	ds_read_b128 v[172:175], v150
	ds_read_b128 v[176:179], v150 offset:1024
	ds_read_b128 v[180:183], v150 offset:2048
	ds_read_b128 v[184:187], v150 offset:3072
	s_add_u32 s44, s44, 0x40000
	s_addc_u32 s45, s45, 0
	s_mov_b32 m0, s50
	ds_read_b128 v[188:191], v154 offset:32768
	ds_read_b128 v[192:195], v154 offset:33792
	ds_read_b128 v[196:199], v154 offset:34816
	ds_read_b128 v[200:203], v154 offset:35840
	ds_read_b128 v[208:211], v154 offset:36864
	ds_read_b128 v[212:215], v154 offset:37888
	ds_read_b128 v[216:219], v154 offset:38912
	ds_read_b128 v[220:223], v154 offset:39936
	global_load_lds_dwordx4 v130, s[44:45]
	s_mov_b32 m0, s51
	s_nop 0
	global_load_lds_dwordx4 v134, s[44:45]
	s_waitcnt vmcnt(8)
	s_waitcnt lgkmcnt(0)
	s_barrier
	s_waitcnt lgkmcnt(0)
	v_mfma_f32_16x16x32_bf16 v[126:129], v[156:159], v[188:191], v[126:129]
	v_mfma_f32_16x16x32_bf16 v[122:125], v[164:167], v[188:191], v[122:125]
	v_mfma_f32_16x16x32_bf16 v[110:113], v[156:159], v[196:199], v[110:113]
	v_mfma_f32_16x16x32_bf16 v[106:109], v[164:167], v[196:199], v[106:109]
	v_mfma_f32_16x16x32_bf16 v[94:97], v[156:159], v[208:211], v[94:97]
	v_mfma_f32_16x16x32_bf16 v[90:93], v[164:167], v[208:211], v[90:93]
	v_mfma_f32_16x16x32_bf16 v[78:81], v[156:159], v[216:219], v[78:81]
	v_mfma_f32_16x16x32_bf16 v[74:77], v[164:167], v[216:219], v[74:77]
	v_mfma_f32_16x16x32_bf16 v[126:129], v[160:163], v[192:195], v[126:129]
	v_mfma_f32_16x16x32_bf16 v[122:125], v[168:171], v[192:195], v[122:125]
	v_mfma_f32_16x16x32_bf16 v[110:113], v[160:163], v[200:203], v[110:113]
	v_mfma_f32_16x16x32_bf16 v[106:109], v[168:171], v[200:203], v[106:109]
	v_mfma_f32_16x16x32_bf16 v[94:97], v[160:163], v[212:215], v[94:97]
	v_mfma_f32_16x16x32_bf16 v[90:93], v[168:171], v[212:215], v[90:93]
	v_mfma_f32_16x16x32_bf16 v[78:81], v[160:163], v[220:223], v[78:81]
	v_mfma_f32_16x16x32_bf16 v[74:77], v[168:171], v[220:223], v[74:77]
	v_mfma_f32_16x16x32_bf16 v[118:121], v[172:175], v[188:191], v[118:121]
	v_mfma_f32_16x16x32_bf16 v[114:117], v[180:183], v[188:191], v[114:117]
	v_mfma_f32_16x16x32_bf16 v[102:105], v[172:175], v[196:199], v[102:105]
	v_mfma_f32_16x16x32_bf16 v[98:101], v[180:183], v[196:199], v[98:101]
	v_mfma_f32_16x16x32_bf16 v[86:89], v[172:175], v[208:211], v[86:89]
	v_mfma_f32_16x16x32_bf16 v[82:85], v[180:183], v[208:211], v[82:85]
	v_mfma_f32_16x16x32_bf16 v[70:73], v[172:175], v[216:219], v[70:73]
	v_mfma_f32_16x16x32_bf16 v[66:69], v[180:183], v[216:219], v[66:69]
	v_mfma_f32_16x16x32_bf16 v[118:121], v[176:179], v[192:195], v[118:121]
	v_mfma_f32_16x16x32_bf16 v[114:117], v[184:187], v[192:195], v[114:117]
	v_mfma_f32_16x16x32_bf16 v[102:105], v[176:179], v[200:203], v[102:105]
	v_mfma_f32_16x16x32_bf16 v[98:101], v[184:187], v[200:203], v[98:101]
	v_mfma_f32_16x16x32_bf16 v[86:89], v[176:179], v[212:215], v[86:89]
	v_mfma_f32_16x16x32_bf16 v[82:85], v[184:187], v[212:215], v[82:85]
	v_mfma_f32_16x16x32_bf16 v[70:73], v[176:179], v[220:223], v[70:73]
	v_mfma_f32_16x16x32_bf16 v[66:69], v[184:187], v[220:223], v[66:69]
	s_barrier
	s_add_i32 s44, s72, s47
	s_mov_b32 m0, s44
	ds_read_b128 v[188:191], v154 offset:49152
	ds_read_b128 v[192:195], v154 offset:50176
	ds_read_b128 v[196:199], v154 offset:51200
	ds_read_b128 v[200:203], v154 offset:52224
	ds_read_b128 v[208:211], v154 offset:53248
	ds_read_b128 v[212:215], v154 offset:54272
	ds_read_b128 v[216:219], v154 offset:55296
	ds_read_b128 v[220:223], v154 offset:56320
	s_add_u32 s98, s40, s12
	s_addc_u32 s99, s41, s13
	global_load_lds_dwordx4 v132, s[98:99]
	s_add_i32 m0, s44, 0x2000
	s_add_u32 s40, s40, 0x40080
	v_lshl_add_u64 v[148:149], v[204:205], 0, s[12:13]
	s_addc_u32 s41, s41, 0
	s_add_i32 s44, s73, s47
	global_load_lds_dwordx4 v[148:149], off
	s_mov_b32 m0, s44
	s_nop 0
	global_load_lds_dwordx4 v132, s[40:41]
	s_add_i32 m0, s44, 0x2000
	s_nop 0
	global_load_lds_dwordx4 v136, s[40:41]
	v_lshl_add_u64 v[148:149], v[224:225], 0, s[12:13]
	s_mov_b32 m0, s61
	s_nop 0
	global_load_lds_dwordx4 v[148:149], off
	v_lshl_add_u64 v[148:149], v[226:227], 0, s[12:13]
	s_mov_b32 m0, s62
	s_nop 0
	global_load_lds_dwordx4 v[148:149], off
	s_waitcnt vmcnt(8)
	s_waitcnt lgkmcnt(0)
	s_barrier
	s_waitcnt lgkmcnt(0)
	v_mfma_f32_16x16x32_bf16 v[62:65], v[156:159], v[188:191], v[62:65]
	v_mfma_f32_16x16x32_bf16 v[58:61], v[164:167], v[188:191], v[58:61]
	v_mfma_f32_16x16x32_bf16 v[46:49], v[156:159], v[196:199], v[46:49]
	v_mfma_f32_16x16x32_bf16 v[42:45], v[164:167], v[196:199], v[42:45]
	v_mfma_f32_16x16x32_bf16 v[30:33], v[156:159], v[208:211], v[30:33]
	v_mfma_f32_16x16x32_bf16 v[26:29], v[164:167], v[208:211], v[26:29]
	v_mfma_f32_16x16x32_bf16 v[14:17], v[156:159], v[216:219], v[14:17]
	v_mfma_f32_16x16x32_bf16 v[10:13], v[164:167], v[216:219], v[10:13]
	v_mfma_f32_16x16x32_bf16 v[62:65], v[160:163], v[192:195], v[62:65]
	v_mfma_f32_16x16x32_bf16 v[58:61], v[168:171], v[192:195], v[58:61]
	v_mfma_f32_16x16x32_bf16 v[46:49], v[160:163], v[200:203], v[46:49]
	v_mfma_f32_16x16x32_bf16 v[42:45], v[168:171], v[200:203], v[42:45]
	v_mfma_f32_16x16x32_bf16 v[30:33], v[160:163], v[212:215], v[30:33]
	v_mfma_f32_16x16x32_bf16 v[26:29], v[168:171], v[212:215], v[26:29]
	v_mfma_f32_16x16x32_bf16 v[14:17], v[160:163], v[220:223], v[14:17]
	v_mfma_f32_16x16x32_bf16 v[10:13], v[168:171], v[220:223], v[10:13]
	v_mfma_f32_16x16x32_bf16 v[54:57], v[172:175], v[188:191], v[54:57]
	v_mfma_f32_16x16x32_bf16 v[50:53], v[180:183], v[188:191], v[50:53]
	v_mfma_f32_16x16x32_bf16 v[38:41], v[172:175], v[196:199], v[38:41]
	v_mfma_f32_16x16x32_bf16 v[34:37], v[180:183], v[196:199], v[34:37]
	v_mfma_f32_16x16x32_bf16 v[22:25], v[172:175], v[208:211], v[22:25]
	v_mfma_f32_16x16x32_bf16 v[18:21], v[180:183], v[208:211], v[18:21]
	v_mfma_f32_16x16x32_bf16 v[6:9], v[172:175], v[216:219], v[6:9]
	v_mfma_f32_16x16x32_bf16 v[2:5], v[180:183], v[216:219], v[2:5]
	v_mfma_f32_16x16x32_bf16 v[54:57], v[176:179], v[192:195], v[54:57]
	v_mfma_f32_16x16x32_bf16 v[50:53], v[184:187], v[192:195], v[50:53]
	v_mfma_f32_16x16x32_bf16 v[38:41], v[176:179], v[200:203], v[38:41]
	v_mfma_f32_16x16x32_bf16 v[34:37], v[184:187], v[200:203], v[34:37]
	v_mfma_f32_16x16x32_bf16 v[22:25], v[176:179], v[212:215], v[22:25]
	v_mfma_f32_16x16x32_bf16 v[18:21], v[184:187], v[212:215], v[18:21]
	v_mfma_f32_16x16x32_bf16 v[6:9], v[176:179], v[220:223], v[6:9]
	v_mfma_f32_16x16x32_bf16 v[2:5], v[184:187], v[220:223], v[2:5]
	s_add_i32 s71, s71, 2
	s_add_u32 s30, s30, 0x100
	s_addc_u32 s31, s31, 0
	s_add_u32 s33, s33, 0x100
	s_addc_u32 s70, s70, 0
	s_cmp_gt_u32 s71, 13
	s_barrier
	s_cbranch_scc0 .LBB0_740
	s_setprio 0
	s_and_b64 vcc, exec, s[14:15]
	s_cbranch_vccz .LBB0_743
	s_barrier

; #define PG8_STAGE(bufoff, gbase, voff) do { _Pragma("unroll") for (int _i = 0; _i < 2; ++_i) \
;         __builtin_amdgcn_global_load_lds((const unsigned*)((const char*)(gbase) + (voff)[_i]), (PG8_LAS unsigned*)(lds + (bufoff) + ldsw + _i * 8192), 16, 0, 0); } while (0)
; #define PG8_LDA(dst, b, h) do { _Pragma("unroll") for (int m = 0; m < 4; ++m) _Pragma("unroll") for (int k = 0; k < 2; ++k) dst[m][k] = *(const PG8_LAS bf16x8*)(lds + PG8_SA(b, h) + aoff + m * 2048 + k * 1024); } while (0)
; #define PG8_LDB(dst, b, h) do { _Pragma("unroll") for (int n = 0; n < 2; ++n) _Pragma("unroll") for (int k = 0; k < 2; ++k) dst[n][k] = *(const PG8_LAS bf16x8*)(lds + PG8_SB(b, h) + boff + n * 2048 + k * 1024); } while (0)
; #define PG8_WAIT_V(n) asm volatile("s_waitcnt vmcnt(" #n ")" ::: "memory")
; #define PG8_WAIT_L(n) asm volatile("s_waitcnt lgkmcnt(" #n ")" ::: "memory")
; #define PG8_BAR __builtin_amdgcn_s_barrier()
; #define PG8_SCHED __builtin_amdgcn_sched_barrier(0)
; template <class Epi, class Sched, bool ALIGN_EPI = false, bool SP2 = false>
; __device__ __forceinline__ void gemm_phase(PG8_LAS unsigned char* lds, const Gemm g, const Sched& S, const Epi& E) {
;     ...
;         const bool has_next = S.next(ui + 1, nxt);
;         const char* nA = has_next ? (const char*)g.A + (size_t)nxt.pm * tstep : cA; const char* nB = has_next ? (const char*)g.Bt + (size_t)nxt.pn * tstep : cB;
;         for (int t = 0; t < nt; t += 2) {
;             const bool last = (t == nt - 2);
;             const char* a1 = cA + (size_t)(t + 1) * kstep;
;             const char* a2 = last ? nA : cA + (size_t)(t + 2) * kstep; const char* b2 = last ? nB : cB + (size_t)(t + 2) * kstep;
;             const char* a3 = a2 + kstep; const char* b3 = b2 + kstep;
;             if (last && has_next) S.a_ready(nxt);
;             if constexpr (SP2) {
;             PG8_LDB(B0, 0, 0); PG8_LDB(B1, 0, 1); PG8_SCHED; PG8_LDA(At, 0, 0); PG8_STAGE(PG8_SA(1, 1), a1 + hstep, voffA);
;             PG8_WAIT_V(8); PG8_WAIT_L(0); PG8_BAR; PG8_MMA(0, 0, At, B0); PG8_MMA(0, 1, At, B1); PG8_BAR; PG8_SCHED;
;             PG8_LDA(At, 0, 1); PG8_STAGE(PG8_SB(0, 0), b2, voffB); PG8_STAGE(PG8_SB(0, 1), b2 + hstep, voffB); PG8_STAGE(PG8_SA(0, 0), a2, voffA);
;             PG8_WAIT_V(8); PG8_WAIT_L(0); PG8_BAR; PG8_MMA(1, 0, At, B0); PG8_MMA(1, 1, At, B1); PG8_BAR; PG8_SCHED;
.LBB0_860:
	s_add_u32 s24, s24, 0xb0080
	s_addc_u32 s25, s25, 0
	s_add_u32 s51, s26, 0x100
	s_addc_u32 s52, s27, 0
	s_mov_b32 s53, -2
	s_bitcmp1_b32 s12, 0
	s_cbranch_scc1 .Lnp_861
	s_setprio 1
.Lnp_861:
	ds_read_b128 v[146:149], v153
	ds_read_b128 v[156:159], v153 offset:1024
	ds_read_b128 v[160:163], v153 offset:2048
	ds_read_b128 v[164:167], v153 offset:3072
	ds_read_b128 v[168:171], v154
	ds_read_b128 v[172:175], v154 offset:1024
	ds_read_b128 v[176:179], v154 offset:2048
	ds_read_b128 v[180:183], v154 offset:3072
	s_add_u32 s26, s24, 0xfff50080
	s_addc_u32 s27, s25, -1
	s_cmp_eq_u32 s53, 40
	s_cselect_b32 s29, s5, s27
	s_cselect_b32 s28, s4, s26
	s_cselect_b32 s27, s23, s52
	s_cselect_b32 s26, s22, s51
	v_lshl_add_u64 v[150:151], s[24:25], 0, v[138:139]
	s_add_i32 m0, s33, 0xc000
	ds_read_b128 v[184:187], v155
	ds_read_b128 v[188:191], v155 offset:1024
	ds_read_b128 v[192:195], v155 offset:2048
	ds_read_b128 v[196:199], v155 offset:3072
	ds_read_b128 v[200:203], v155 offset:4096
	ds_read_b128 v[204:207], v155 offset:5120
	ds_read_b128 v[208:211], v155 offset:6144
	ds_read_b128 v[212:215], v155 offset:7168
	global_load_lds_dwordx4 v[150:151], off
	v_lshl_add_u64 v[150:151], s[24:25], 0, v[140:141]
	s_add_i32 m0, s33, 0xe000
	s_nop 0
	global_load_lds_dwordx4 v[150:151], off
	s_waitcnt vmcnt(8)
	s_waitcnt lgkmcnt(0)
	s_barrier
	s_waitcnt lgkmcnt(0)
	v_mfma_f32_16x16x32_bf16 v[124:127], v[146:149], v[184:187], 0
	v_mfma_f32_16x16x32_bf16 v[120:123], v[160:163], v[184:187], 0
	v_mfma_f32_16x16x32_bf16 v[108:111], v[146:149], v[192:195], 0
	v_mfma_f32_16x16x32_bf16 v[104:107], v[160:163], v[192:195], 0
	v_mfma_f32_16x16x32_bf16 v[92:95], v[146:149], v[200:203], 0
	v_mfma_f32_16x16x32_bf16 v[88:91], v[160:163], v[200:203], 0
	v_mfma_f32_16x16x32_bf16 v[76:79], v[146:149], v[208:211], 0
	v_mfma_f32_16x16x32_bf16 v[72:75], v[160:163], v[208:211], 0
	v_mfma_f32_16x16x32_bf16 v[124:127], v[156:159], v[188:191], v[124:127]
	v_mfma_f32_16x16x32_bf16 v[120:123], v[164:167], v[188:191], v[120:123]
	v_mfma_f32_16x16x32_bf16 v[108:111], v[156:159], v[196:199], v[108:111]
	v_mfma_f32_16x16x32_bf16 v[104:107], v[164:167], v[196:199], v[104:107]
	v_mfma_f32_16x16x32_bf16 v[92:95], v[156:159], v[204:207], v[92:95]
	v_mfma_f32_16x16x32_bf16 v[88:91], v[164:167], v[204:207], v[88:91]
	v_mfma_f32_16x16x32_bf16 v[76:79], v[156:159], v[212:215], v[76:79]
	v_mfma_f32_16x16x32_bf16 v[72:75], v[164:167], v[212:215], v[72:75]
	v_mfma_f32_16x16x32_bf16 v[116:119], v[168:171], v[184:187], 0
	v_mfma_f32_16x16x32_bf16 v[112:115], v[176:179], v[184:187], 0
	v_mfma_f32_16x16x32_bf16 v[100:103], v[168:171], v[192:195], 0
	v_mfma_f32_16x16x32_bf16 v[96:99], v[176:179], v[192:195], 0
	v_mfma_f32_16x16x32_bf16 v[84:87], v[168:171], v[200:203], 0
	v_mfma_f32_16x16x32_bf16 v[80:83], v[176:179], v[200:203], 0
	v_mfma_f32_16x16x32_bf16 v[68:71], v[168:171], v[208:211], 0
	v_mfma_f32_16x16x32_bf16 v[64:67], v[176:179], v[208:211], 0
	v_mfma_f32_16x16x32_bf16 v[116:119], v[172:175], v[188:191], v[116:119]
	v_mfma_f32_16x16x32_bf16 v[112:115], v[180:183], v[188:191], v[112:115]
	v_mfma_f32_16x16x32_bf16 v[100:103], v[172:175], v[196:199], v[100:103]
	v_mfma_f32_16x16x32_bf16 v[96:99], v[180:183], v[196:199], v[96:99]
	v_mfma_f32_16x16x32_bf16 v[84:87], v[172:175], v[204:207], v[84:87]
	v_mfma_f32_16x16x32_bf16 v[80:83], v[180:183], v[204:207], v[80:83]
	v_mfma_f32_16x16x32_bf16 v[68:71], v[172:175], v[212:215], v[68:71]
	v_mfma_f32_16x16x32_bf16 v[64:67], v[180:183], v[212:215], v[64:67]
	s_barrier
	s_add_i32 s56, s45, s31
	s_mov_b32 m0, s56
	ds_read_b128 v[184:187], v155 offset:16384
	ds_read_b128 v[188:191], v155 offset:17408
	ds_read_b128 v[192:195], v155 offset:18432
	ds_read_b128 v[196:199], v155 offset:19456
	ds_read_b128 v[200:203], v155 offset:20480
	ds_read_b128 v[204:207], v155 offset:21504
	ds_read_b128 v[208:211], v155 offset:22528
	ds_read_b128 v[212:215], v155 offset:23552
	global_load_lds_dwordx4 v130, s[26:27]
	s_add_i32 m0, s56, 0x2000
	s_add_u32 s56, s26, 0xb0000
	v_lshl_add_u64 v[216:217], s[26:27], 0, v[134:135]
	s_addc_u32 s57, s27, 0
	s_add_i32 s58, s46, s31
	global_load_lds_dwordx4 v134, s[26:27]
	s_mov_b32 m0, s58
	v_lshl_add_u64 v[220:221], s[28:29], 0, v[132:133]
	global_load_lds_dwordx4 v130, s[56:57]
	s_add_i32 m0, s58, 0x2000
	s_nop 0
	global_load_lds_dwordx4 v134, s[56:57]
	v_lshl_add_u64 v[218:219], s[28:29], 0, v[128:129]
	s_mov_b32 m0, s33
	s_nop 0
	global_load_lds_dwordx4 v128, s[28:29]
	s_mov_b32 m0, s36
	s_nop 0
	global_load_lds_dwordx4 v132, s[28:29]
	s_waitcnt vmcnt(8)
	s_waitcnt lgkmcnt(0)
	s_barrier
; #define PG8_STAGE(bufoff, gbase, voff) do { _Pragma("unroll") for (int _i = 0; _i < 2; ++_i) \
;         __builtin_amdgcn_global_load_lds((const unsigned*)((const char*)(gbase) + (voff)[_i]), (PG8_LAS unsigned*)(lds + (bufoff) + ldsw + _i * 8192), 16, 0, 0); } while (0)
; #define PG8_LDA(dst, b, h) do { _Pragma("unroll") for (int m = 0; m < 4; ++m) _Pragma("unroll") for (int k = 0; k < 2; ++k) dst[m][k] = *(const PG8_LAS bf16x8*)(lds + PG8_SA(b, h) + aoff + m * 2048 + k * 1024); } while (0)
; #define PG8_LDB(dst, b, h) do { _Pragma("unroll") for (int n = 0; n < 2; ++n) _Pragma("unroll") for (int k = 0; k < 2; ++k) dst[n][k] = *(const PG8_LAS bf16x8*)(lds + PG8_SB(b, h) + boff + n * 2048 + k * 1024); } while (0)
; #define PG8_MMA(ai, bj, At, Bt) do { __builtin_amdgcn_s_setprio(1); _Pragma("unroll") for (int m = 0; m < 4; ++m) _Pragma("unroll") for (int n = 0; n < 2; ++n) _Pragma("unroll") for (int k = 0; k < 2; ++k) \
;         acc[ai][bj][m][n] = __builtin_amdgcn_mfma_f32_16x16x32_bf16(Bt[n][k], At[m][k], acc[ai][bj][m][n], 0, 0, 0); __builtin_amdgcn_s_setprio(0); } while (0)
; #define PG8_WAIT_V(n) asm volatile("s_waitcnt vmcnt(" #n ")" ::: "memory")
; #define PG8_WAIT_L(n) asm volatile("s_waitcnt lgkmcnt(" #n ")" ::: "memory")
; #define PG8_BAR __builtin_amdgcn_s_barrier()
; #define PG8_SCHED __builtin_amdgcn_sched_barrier(0)
; template <class Epi, class Sched, bool ALIGN_EPI = false, bool SP2 = false>
; __device__ __forceinline__ void gemm_phase(PG8_LAS unsigned char* lds, const Gemm g, const Sched& S, const Epi& E) {
;     ...
;             PG8_WAIT_V(8); PG8_WAIT_L(0); PG8_BAR; PG8_MMA(0, 0, At, B0); PG8_MMA(0, 1, At, B1); PG8_BAR; PG8_SCHED;
;             PG8_LDA(At, 0, 1); PG8_STAGE(PG8_SB(0, 0), b2, voffB); PG8_STAGE(PG8_SB(0, 1), b2 + hstep, voffB); PG8_STAGE(PG8_SA(0, 0), a2, voffA);
;             PG8_WAIT_V(8); PG8_WAIT_L(0); PG8_BAR; PG8_MMA(1, 0, At, B0); PG8_MMA(1, 1, At, B1); PG8_BAR; PG8_SCHED;
;             PG8_LDB(B0, 1, 0); PG8_LDB(B1, 1, 1); PG8_SCHED; PG8_LDA(At, 1, 0); PG8_STAGE(PG8_SA(0, 1), a2 + hstep, voffA);
;             PG8_WAIT_V(8); PG8_WAIT_L(0); PG8_BAR; PG8_MMA(0, 0, At, B0); PG8_MMA(0, 1, At, B1); PG8_BAR; PG8_SCHED;
	s_waitcnt lgkmcnt(0)
	v_mfma_f32_16x16x32_bf16 v[60:63], v[146:149], v[184:187], 0
	v_mfma_f32_16x16x32_bf16 v[56:59], v[160:163], v[184:187], 0
	v_mfma_f32_16x16x32_bf16 v[44:47], v[146:149], v[192:195], 0
	v_mfma_f32_16x16x32_bf16 v[40:43], v[160:163], v[192:195], 0
	v_mfma_f32_16x16x32_bf16 v[28:31], v[146:149], v[200:203], 0
	v_mfma_f32_16x16x32_bf16 v[24:27], v[160:163], v[200:203], 0
	v_mfma_f32_16x16x32_bf16 v[12:15], v[146:149], v[208:211], 0
	v_mfma_f32_16x16x32_bf16 v[8:11], v[160:163], v[208:211], 0
	v_mfma_f32_16x16x32_bf16 v[60:63], v[156:159], v[188:191], v[60:63]
	v_mfma_f32_16x16x32_bf16 v[56:59], v[164:167], v[188:191], v[56:59]
	v_mfma_f32_16x16x32_bf16 v[44:47], v[156:159], v[196:199], v[44:47]
	v_mfma_f32_16x16x32_bf16 v[40:43], v[164:167], v[196:199], v[40:43]
	v_mfma_f32_16x16x32_bf16 v[28:31], v[156:159], v[204:207], v[28:31]
	v_mfma_f32_16x16x32_bf16 v[24:27], v[164:167], v[204:207], v[24:27]
	v_mfma_f32_16x16x32_bf16 v[12:15], v[156:159], v[212:215], v[12:15]
	v_mfma_f32_16x16x32_bf16 v[8:11], v[164:167], v[212:215], v[8:11]
	v_mfma_f32_16x16x32_bf16 v[52:55], v[168:171], v[184:187], 0
	v_mfma_f32_16x16x32_bf16 v[48:51], v[176:179], v[184:187], 0
	v_mfma_f32_16x16x32_bf16 v[36:39], v[168:171], v[192:195], 0
	v_mfma_f32_16x16x32_bf16 v[32:35], v[176:179], v[192:195], 0
	v_mfma_f32_16x16x32_bf16 v[20:23], v[168:171], v[200:203], 0
	v_mfma_f32_16x16x32_bf16 v[16:19], v[176:179], v[200:203], 0
	v_mfma_f32_16x16x32_bf16 v[4:7], v[168:171], v[208:211], 0
	v_mfma_f32_16x16x32_bf16 v[0:3], v[176:179], v[208:211], 0
	v_mfma_f32_16x16x32_bf16 v[52:55], v[172:175], v[188:191], v[52:55]
	v_mfma_f32_16x16x32_bf16 v[48:51], v[180:183], v[188:191], v[48:51]
	v_mfma_f32_16x16x32_bf16 v[36:39], v[172:175], v[196:199], v[36:39]
	v_mfma_f32_16x16x32_bf16 v[32:35], v[180:183], v[196:199], v[32:35]
	v_mfma_f32_16x16x32_bf16 v[20:23], v[172:175], v[204:207], v[20:23]
	v_mfma_f32_16x16x32_bf16 v[16:19], v[180:183], v[204:207], v[16:19]
	v_mfma_f32_16x16x32_bf16 v[4:7], v[172:175], v[212:215], v[4:7]
	v_mfma_f32_16x16x32_bf16 v[0:3], v[180:183], v[212:215], v[0:3]
	s_barrier
	s_add_i32 s56, 0, 0x18000
	s_add_i32 s57, 0, 0x1c000
	v_add_u32_e32 v164, s56, v152
	v_add_u32_e32 v180, s57, v152
	ds_read_b128 v[146:149], v164
	ds_read_b128 v[156:159], v164 offset:1024
	ds_read_b128 v[160:163], v164 offset:2048
	ds_read_b128 v[164:167], v164 offset:3072
	ds_read_b128 v[168:171], v180
	ds_read_b128 v[172:175], v180 offset:1024
	ds_read_b128 v[176:179], v180 offset:2048
	ds_read_b128 v[180:183], v180 offset:3072
	s_add_u32 s28, s28, 0xb0000
	s_addc_u32 s29, s29, 0
	s_mov_b32 m0, s37
	ds_read_b128 v[184:187], v155 offset:32768
	ds_read_b128 v[188:191], v155 offset:33792
	ds_read_b128 v[192:195], v155 offset:34816
	ds_read_b128 v[196:199], v155 offset:35840
	ds_read_b128 v[200:203], v155 offset:36864
	ds_read_b128 v[204:207], v155 offset:37888
	ds_read_b128 v[208:211], v155 offset:38912
	ds_read_b128 v[212:215], v155 offset:39936
	global_load_lds_dwordx4 v128, s[28:29]
	s_mov_b32 m0, s38
	s_nop 0
	global_load_lds_dwordx4 v132, s[28:29]
	s_waitcnt vmcnt(8)
	s_waitcnt lgkmcnt(0)
	s_barrier
	s_waitcnt lgkmcnt(0)
	v_mfma_f32_16x16x32_bf16 v[124:127], v[146:149], v[184:187], v[124:127]
	v_mfma_f32_16x16x32_bf16 v[120:123], v[160:163], v[184:187], v[120:123]
	v_mfma_f32_16x16x32_bf16 v[108:111], v[146:149], v[192:195], v[108:111]
	v_mfma_f32_16x16x32_bf16 v[104:107], v[160:163], v[192:195], v[104:107]
	v_mfma_f32_16x16x32_bf16 v[92:95], v[146:149], v[200:203], v[92:95]
	v_mfma_f32_16x16x32_bf16 v[88:91], v[160:163], v[200:203], v[88:91]
	v_mfma_f32_16x16x32_bf16 v[76:79], v[146:149], v[208:211], v[76:79]
	v_mfma_f32_16x16x32_bf16 v[72:75], v[160:163], v[208:211], v[72:75]
	v_mfma_f32_16x16x32_bf16 v[124:127], v[156:159], v[188:191], v[124:127]
	v_mfma_f32_16x16x32_bf16 v[120:123], v[164:167], v[188:191], v[120:123]
	v_mfma_f32_16x16x32_bf16 v[108:111], v[156:159], v[196:199], v[108:111]
	v_mfma_f32_16x16x32_bf16 v[104:107], v[164:167], v[196:199], v[104:107]
	v_mfma_f32_16x16x32_bf16 v[92:95], v[156:159], v[204:207], v[92:95]
	v_mfma_f32_16x16x32_bf16 v[88:91], v[164:167], v[204:207], v[88:91]
	v_mfma_f32_16x16x32_bf16 v[76:79], v[156:159], v[212:215], v[76:79]
	v_mfma_f32_16x16x32_bf16 v[72:75], v[164:167], v[212:215], v[72:75]
	v_mfma_f32_16x16x32_bf16 v[116:119], v[168:171], v[184:187], v[116:119]
	v_mfma_f32_16x16x32_bf16 v[112:115], v[176:179], v[184:187], v[112:115]
	v_mfma_f32_16x16x32_bf16 v[100:103], v[168:171], v[192:195], v[100:103]
	v_mfma_f32_16x16x32_bf16 v[96:99], v[176:179], v[192:195], v[96:99]
	v_mfma_f32_16x16x32_bf16 v[84:87], v[168:171], v[200:203], v[84:87]
	v_mfma_f32_16x16x32_bf16 v[80:83], v[176:179], v[200:203], v[80:83]
	v_mfma_f32_16x16x32_bf16 v[68:71], v[168:171], v[208:211], v[68:71]
	v_mfma_f32_16x16x32_bf16 v[64:67], v[176:179], v[208:211], v[64:67]
	v_mfma_f32_16x16x32_bf16 v[116:119], v[172:175], v[188:191], v[116:119]
	v_mfma_f32_16x16x32_bf16 v[112:115], v[180:183], v[188:191], v[112:115]
	v_mfma_f32_16x16x32_bf16 v[100:103], v[172:175], v[196:199], v[100:103]
	v_mfma_f32_16x16x32_bf16 v[96:99], v[180:183], v[196:199], v[96:99]
	v_mfma_f32_16x16x32_bf16 v[84:87], v[172:175], v[204:207], v[84:87]
	v_mfma_f32_16x16x32_bf16 v[80:83], v[180:183], v[204:207], v[80:83]
	v_mfma_f32_16x16x32_bf16 v[68:71], v[172:175], v[212:215], v[68:71]
	v_mfma_f32_16x16x32_bf16 v[64:67], v[180:183], v[212:215], v[64:67]
	s_barrier
; #define PG8_STAGE(bufoff, gbase, voff) do { _Pragma("unroll") for (int _i = 0; _i < 2; ++_i) \
;         __builtin_amdgcn_global_load_lds((const unsigned*)((const char*)(gbase) + (voff)[_i]), (PG8_LAS unsigned*)(lds + (bufoff) + ldsw + _i * 8192), 16, 0, 0); } while (0)
; #define PG8_LDA(dst, b, h) do { _Pragma("unroll") for (int m = 0; m < 4; ++m) _Pragma("unroll") for (int k = 0; k < 2; ++k) dst[m][k] = *(const PG8_LAS bf16x8*)(lds + PG8_SA(b, h) + aoff + m * 2048 + k * 1024); } while (0)
; #define PG8_LDB(dst, b, h) do { _Pragma("unroll") for (int n = 0; n < 2; ++n) _Pragma("unroll") for (int k = 0; k < 2; ++k) dst[n][k] = *(const PG8_LAS bf16x8*)(lds + PG8_SB(b, h) + boff + n * 2048 + k * 1024); } while (0)
; #define PG8_MMA(ai, bj, At, Bt) do { __builtin_amdgcn_s_setprio(1); _Pragma("unroll") for (int m = 0; m < 4; ++m) _Pragma("unroll") for (int n = 0; n < 2; ++n) _Pragma("unroll") for (int k = 0; k < 2; ++k) \
;         acc[ai][bj][m][n] = __builtin_amdgcn_mfma_f32_16x16x32_bf16(Bt[n][k], At[m][k], acc[ai][bj][m][n], 0, 0, 0); __builtin_amdgcn_s_setprio(0); } while (0)
; #define PG8_WAIT_V(n) asm volatile("s_waitcnt vmcnt(" #n ")" ::: "memory")
; #define PG8_WAIT_L(n) asm volatile("s_waitcnt lgkmcnt(" #n ")" ::: "memory")
; #define PG8_BAR __builtin_amdgcn_s_barrier()
; #define PG8_SCHED __builtin_amdgcn_sched_barrier(0)
; template <class Epi, class Sched, bool ALIGN_EPI = false, bool SP2 = false>
; __device__ __forceinline__ void gemm_phase(PG8_LAS unsigned char* lds, const Gemm g, const Sched& S, const Epi& E) {
;     ...
;             PG8_LDB(B0, 0, 0); PG8_LDB(B1, 0, 1); PG8_SCHED; PG8_LDA(At, 0, 0); PG8_STAGE(PG8_SA(1, 1), a1 + hstep, voffA);
;             PG8_WAIT_V(8); PG8_WAIT_L(0); PG8_BAR; PG8_MMA(0, 0, At, B0); PG8_MMA(0, 1, At, B1); PG8_BAR; PG8_SCHED;
;     ...
;             PG8_LDA(At, 1, 1); PG8_STAGE(PG8_SB(1, 0), b3, voffB); PG8_STAGE(PG8_SB(1, 1), b3 + hstep, voffB); PG8_STAGE(PG8_SA(1, 0), a3, voffA);
;             PG8_WAIT_V(8); PG8_WAIT_L(0); PG8_BAR; PG8_MMA(1, 0, At, B0); PG8_MMA(1, 1, At, B1); PG8_BAR; PG8_SCHED;
	s_add_i32 s28, s56, s31
	s_mov_b32 m0, s28
	ds_read_b128 v[184:187], v155 offset:49152
	ds_read_b128 v[188:191], v155 offset:50176
	ds_read_b128 v[192:195], v155 offset:51200
	ds_read_b128 v[196:199], v155 offset:52224
	ds_read_b128 v[200:203], v155 offset:53248
	ds_read_b128 v[204:207], v155 offset:54272
	ds_read_b128 v[208:211], v155 offset:55296
	ds_read_b128 v[212:215], v155 offset:56320
	s_add_u32 s98, s26, s10
	s_addc_u32 s99, s27, s11
	global_load_lds_dwordx4 v130, s[98:99]
	s_add_i32 m0, s28, 0x2000
	s_add_u32 s26, s26, 0xb0080
	v_lshl_add_u64 v[150:151], v[216:217], 0, s[10:11]
	s_addc_u32 s27, s27, 0
	s_add_i32 s28, s57, s31
	global_load_lds_dwordx4 v[150:151], off
	s_mov_b32 m0, s28
	s_nop 0
	global_load_lds_dwordx4 v130, s[26:27]
	s_add_i32 m0, s28, 0x2000
	s_nop 0
	global_load_lds_dwordx4 v134, s[26:27]
	v_lshl_add_u64 v[150:151], v[218:219], 0, s[10:11]
	s_mov_b32 m0, s40
	s_nop 0
	global_load_lds_dwordx4 v[150:151], off
	v_lshl_add_u64 v[150:151], v[220:221], 0, s[10:11]
	s_mov_b32 m0, s41
	s_nop 0
	global_load_lds_dwordx4 v[150:151], off
	s_waitcnt vmcnt(8)
	s_waitcnt lgkmcnt(0)
	s_barrier
	s_waitcnt lgkmcnt(0)
	v_mfma_f32_16x16x32_bf16 v[60:63], v[146:149], v[184:187], v[60:63]
	v_mfma_f32_16x16x32_bf16 v[56:59], v[160:163], v[184:187], v[56:59]
	v_mfma_f32_16x16x32_bf16 v[44:47], v[146:149], v[192:195], v[44:47]
	v_mfma_f32_16x16x32_bf16 v[40:43], v[160:163], v[192:195], v[40:43]
	v_mfma_f32_16x16x32_bf16 v[28:31], v[146:149], v[200:203], v[28:31]
	v_mfma_f32_16x16x32_bf16 v[24:27], v[160:163], v[200:203], v[24:27]
	v_mfma_f32_16x16x32_bf16 v[12:15], v[146:149], v[208:211], v[12:15]
	v_mfma_f32_16x16x32_bf16 v[8:11], v[160:163], v[208:211], v[8:11]
	v_mfma_f32_16x16x32_bf16 v[60:63], v[156:159], v[188:191], v[60:63]
	v_mfma_f32_16x16x32_bf16 v[56:59], v[164:167], v[188:191], v[56:59]
	v_mfma_f32_16x16x32_bf16 v[44:47], v[156:159], v[196:199], v[44:47]
	v_mfma_f32_16x16x32_bf16 v[40:43], v[164:167], v[196:199], v[40:43]
	v_mfma_f32_16x16x32_bf16 v[28:31], v[156:159], v[204:207], v[28:31]
	v_mfma_f32_16x16x32_bf16 v[24:27], v[164:167], v[204:207], v[24:27]
	v_mfma_f32_16x16x32_bf16 v[12:15], v[156:159], v[212:215], v[12:15]
	v_mfma_f32_16x16x32_bf16 v[8:11], v[164:167], v[212:215], v[8:11]
	v_mfma_f32_16x16x32_bf16 v[52:55], v[168:171], v[184:187], v[52:55]
	v_mfma_f32_16x16x32_bf16 v[48:51], v[176:179], v[184:187], v[48:51]
	v_mfma_f32_16x16x32_bf16 v[36:39], v[168:171], v[192:195], v[36:39]
	v_mfma_f32_16x16x32_bf16 v[32:35], v[176:179], v[192:195], v[32:35]
	v_mfma_f32_16x16x32_bf16 v[20:23], v[168:171], v[200:203], v[20:23]
	v_mfma_f32_16x16x32_bf16 v[16:19], v[176:179], v[200:203], v[16:19]
	v_mfma_f32_16x16x32_bf16 v[4:7], v[168:171], v[208:211], v[4:7]
	v_mfma_f32_16x16x32_bf16 v[0:3], v[176:179], v[208:211], v[0:3]
	v_mfma_f32_16x16x32_bf16 v[52:55], v[172:175], v[188:191], v[52:55]
	v_mfma_f32_16x16x32_bf16 v[48:51], v[180:183], v[188:191], v[48:51]
	v_mfma_f32_16x16x32_bf16 v[36:39], v[172:175], v[196:199], v[36:39]
	v_mfma_f32_16x16x32_bf16 v[32:35], v[180:183], v[196:199], v[32:35]
	v_mfma_f32_16x16x32_bf16 v[20:23], v[172:175], v[204:207], v[20:23]
	v_mfma_f32_16x16x32_bf16 v[16:19], v[180:183], v[204:207], v[16:19]
	v_mfma_f32_16x16x32_bf16 v[4:7], v[172:175], v[212:215], v[4:7]
	v_mfma_f32_16x16x32_bf16 v[0:3], v[180:183], v[212:215], v[0:3]
	s_add_i32 s53, s53, 2
	s_add_u32 s24, s24, 0x100
	s_addc_u32 s25, s25, 0
	s_add_u32 s51, s51, 0x100
	s_addc_u32 s52, s52, 0
	s_cmp_gt_u32 s53, 41
	s_barrier
.LBB0_861:
	ds_read_b128 v[146:149], v153
	ds_read_b128 v[156:159], v153 offset:1024
	ds_read_b128 v[160:163], v153 offset:2048
	ds_read_b128 v[164:167], v153 offset:3072
	ds_read_b128 v[168:171], v154
	ds_read_b128 v[172:175], v154 offset:1024
	ds_read_b128 v[176:179], v154 offset:2048
	ds_read_b128 v[180:183], v154 offset:3072
	s_add_u32 s26, s24, 0xfff50080
	s_addc_u32 s27, s25, -1
	s_cmp_eq_u32 s53, 40
	s_cselect_b32 s29, s5, s27
	s_cselect_b32 s28, s4, s26
	s_cselect_b32 s27, s23, s52
	s_cselect_b32 s26, s22, s51
	v_lshl_add_u64 v[150:151], s[24:25], 0, v[138:139]
	s_add_i32 m0, s33, 0xc000
	ds_read_b128 v[184:187], v155
	ds_read_b128 v[188:191], v155 offset:1024
	ds_read_b128 v[192:195], v155 offset:2048
	ds_read_b128 v[196:199], v155 offset:3072
	ds_read_b128 v[200:203], v155 offset:4096
	ds_read_b128 v[204:207], v155 offset:5120
	ds_read_b128 v[208:211], v155 offset:6144
	ds_read_b128 v[212:215], v155 offset:7168
	global_load_lds_dwordx4 v[150:151], off
	v_lshl_add_u64 v[150:151], s[24:25], 0, v[140:141]
	s_add_i32 m0, s33, 0xe000
	s_nop 0
	global_load_lds_dwordx4 v[150:151], off
	s_waitcnt vmcnt(8)
	s_waitcnt lgkmcnt(0)
	s_barrier
; #define PG8_STAGE(bufoff, gbase, voff) do { _Pragma("unroll") for (int _i = 0; _i < 2; ++_i) \
;         __builtin_amdgcn_global_load_lds((const unsigned*)((const char*)(gbase) + (voff)[_i]), (PG8_LAS unsigned*)(lds + (bufoff) + ldsw + _i * 8192), 16, 0, 0); } while (0)
; #define PG8_LDA(dst, b, h) do { _Pragma("unroll") for (int m = 0; m < 4; ++m) _Pragma("unroll") for (int k = 0; k < 2; ++k) dst[m][k] = *(const PG8_LAS bf16x8*)(lds + PG8_SA(b, h) + aoff + m * 2048 + k * 1024); } while (0)
; #define PG8_MMA(ai, bj, At, Bt) do { __builtin_amdgcn_s_setprio(1); _Pragma("unroll") for (int m = 0; m < 4; ++m) _Pragma("unroll") for (int n = 0; n < 2; ++n) _Pragma("unroll") for (int k = 0; k < 2; ++k) \
;         acc[ai][bj][m][n] = __builtin_amdgcn_mfma_f32_16x16x32_bf16(Bt[n][k], At[m][k], acc[ai][bj][m][n], 0, 0, 0); __builtin_amdgcn_s_setprio(0); } while (0)
; #define PG8_WAIT_V(n) asm volatile("s_waitcnt vmcnt(" #n ")" ::: "memory")
; #define PG8_WAIT_L(n) asm volatile("s_waitcnt lgkmcnt(" #n ")" ::: "memory")
; #define PG8_BAR __builtin_amdgcn_s_barrier()
; #define PG8_SCHED __builtin_amdgcn_sched_barrier(0)
; template <class Epi, class Sched, bool ALIGN_EPI = false, bool SP2 = false>
; __device__ __forceinline__ void gemm_phase(PG8_LAS unsigned char* lds, const Gemm g, const Sched& S, const Epi& E) {
;     ...
;             PG8_WAIT_V(8); PG8_WAIT_L(0); PG8_BAR; PG8_MMA(0, 0, At, B0); PG8_MMA(0, 1, At, B1); PG8_BAR; PG8_SCHED;
;             PG8_LDA(At, 0, 1); PG8_STAGE(PG8_SB(0, 0), b2, voffB); PG8_STAGE(PG8_SB(0, 1), b2 + hstep, voffB); PG8_STAGE(PG8_SA(0, 0), a2, voffA);
;             PG8_WAIT_V(8); PG8_WAIT_L(0); PG8_BAR; PG8_MMA(1, 0, At, B0); PG8_MMA(1, 1, At, B1); PG8_BAR; PG8_SCHED;
	s_waitcnt lgkmcnt(0)
	v_mfma_f32_16x16x32_bf16 v[124:127], v[146:149], v[184:187], v[124:127]
	v_mfma_f32_16x16x32_bf16 v[120:123], v[160:163], v[184:187], v[120:123]
	v_mfma_f32_16x16x32_bf16 v[108:111], v[146:149], v[192:195], v[108:111]
	v_mfma_f32_16x16x32_bf16 v[104:107], v[160:163], v[192:195], v[104:107]
	v_mfma_f32_16x16x32_bf16 v[92:95], v[146:149], v[200:203], v[92:95]
	v_mfma_f32_16x16x32_bf16 v[88:91], v[160:163], v[200:203], v[88:91]
	v_mfma_f32_16x16x32_bf16 v[76:79], v[146:149], v[208:211], v[76:79]
	v_mfma_f32_16x16x32_bf16 v[72:75], v[160:163], v[208:211], v[72:75]
	v_mfma_f32_16x16x32_bf16 v[124:127], v[156:159], v[188:191], v[124:127]
	v_mfma_f32_16x16x32_bf16 v[120:123], v[164:167], v[188:191], v[120:123]
	v_mfma_f32_16x16x32_bf16 v[108:111], v[156:159], v[196:199], v[108:111]
	v_mfma_f32_16x16x32_bf16 v[104:107], v[164:167], v[196:199], v[104:107]
	v_mfma_f32_16x16x32_bf16 v[92:95], v[156:159], v[204:207], v[92:95]
	v_mfma_f32_16x16x32_bf16 v[88:91], v[164:167], v[204:207], v[88:91]
	v_mfma_f32_16x16x32_bf16 v[76:79], v[156:159], v[212:215], v[76:79]
	v_mfma_f32_16x16x32_bf16 v[72:75], v[164:167], v[212:215], v[72:75]
	v_mfma_f32_16x16x32_bf16 v[116:119], v[168:171], v[184:187], v[116:119]
	v_mfma_f32_16x16x32_bf16 v[112:115], v[176:179], v[184:187], v[112:115]
	v_mfma_f32_16x16x32_bf16 v[100:103], v[168:171], v[192:195], v[100:103]
	v_mfma_f32_16x16x32_bf16 v[96:99], v[176:179], v[192:195], v[96:99]
	v_mfma_f32_16x16x32_bf16 v[84:87], v[168:171], v[200:203], v[84:87]
	v_mfma_f32_16x16x32_bf16 v[80:83], v[176:179], v[200:203], v[80:83]
	v_mfma_f32_16x16x32_bf16 v[68:71], v[168:171], v[208:211], v[68:71]
	v_mfma_f32_16x16x32_bf16 v[64:67], v[176:179], v[208:211], v[64:67]
	v_mfma_f32_16x16x32_bf16 v[116:119], v[172:175], v[188:191], v[116:119]
	v_mfma_f32_16x16x32_bf16 v[112:115], v[180:183], v[188:191], v[112:115]
	v_mfma_f32_16x16x32_bf16 v[100:103], v[172:175], v[196:199], v[100:103]
	v_mfma_f32_16x16x32_bf16 v[96:99], v[180:183], v[196:199], v[96:99]
	v_mfma_f32_16x16x32_bf16 v[84:87], v[172:175], v[204:207], v[84:87]
	v_mfma_f32_16x16x32_bf16 v[80:83], v[180:183], v[204:207], v[80:83]
	v_mfma_f32_16x16x32_bf16 v[68:71], v[172:175], v[212:215], v[68:71]
	v_mfma_f32_16x16x32_bf16 v[64:67], v[180:183], v[212:215], v[64:67]
	s_barrier
	s_add_i32 s56, s45, s31
	s_mov_b32 m0, s56
	ds_read_b128 v[184:187], v155 offset:16384
	ds_read_b128 v[188:191], v155 offset:17408
	ds_read_b128 v[192:195], v155 offset:18432
	ds_read_b128 v[196:199], v155 offset:19456
	ds_read_b128 v[200:203], v155 offset:20480
	ds_read_b128 v[204:207], v155 offset:21504
	ds_read_b128 v[208:211], v155 offset:22528
	ds_read_b128 v[212:215], v155 offset:23552
	global_load_lds_dwordx4 v130, s[26:27]
	s_add_i32 m0, s56, 0x2000
	s_add_u32 s56, s26, 0xb0000
	v_lshl_add_u64 v[216:217], s[26:27], 0, v[134:135]
	s_addc_u32 s57, s27, 0
	s_add_i32 s58, s46, s31
	global_load_lds_dwordx4 v134, s[26:27]
	s_mov_b32 m0, s58
	v_lshl_add_u64 v[220:221], s[28:29], 0, v[132:133]
	global_load_lds_dwordx4 v130, s[56:57]
	s_add_i32 m0, s58, 0x2000
	s_nop 0
	global_load_lds_dwordx4 v134, s[56:57]
	v_lshl_add_u64 v[218:219], s[28:29], 0, v[128:129]
	s_mov_b32 m0, s33
	s_nop 0
	global_load_lds_dwordx4 v128, s[28:29]
	s_mov_b32 m0, s36
	s_nop 0
	global_load_lds_dwordx4 v132, s[28:29]
	s_waitcnt vmcnt(8)
	s_waitcnt lgkmcnt(0)
	s_barrier
	s_waitcnt lgkmcnt(0)
	v_mfma_f32_16x16x32_bf16 v[60:63], v[146:149], v[184:187], v[60:63]
	v_mfma_f32_16x16x32_bf16 v[56:59], v[160:163], v[184:187], v[56:59]
	v_mfma_f32_16x16x32_bf16 v[44:47], v[146:149], v[192:195], v[44:47]
	v_mfma_f32_16x16x32_bf16 v[40:43], v[160:163], v[192:195], v[40:43]
	v_mfma_f32_16x16x32_bf16 v[28:31], v[146:149], v[200:203], v[28:31]
	v_mfma_f32_16x16x32_bf16 v[24:27], v[160:163], v[200:203], v[24:27]
	v_mfma_f32_16x16x32_bf16 v[12:15], v[146:149], v[208:211], v[12:15]
	v_mfma_f32_16x16x32_bf16 v[8:11], v[160:163], v[208:211], v[8:11]
	v_mfma_f32_16x16x32_bf16 v[60:63], v[156:159], v[188:191], v[60:63]
	v_mfma_f32_16x16x32_bf16 v[56:59], v[164:167], v[188:191], v[56:59]
	v_mfma_f32_16x16x32_bf16 v[44:47], v[156:159], v[196:199], v[44:47]
	v_mfma_f32_16x16x32_bf16 v[40:43], v[164:167], v[196:199], v[40:43]
	v_mfma_f32_16x16x32_bf16 v[28:31], v[156:159], v[204:207], v[28:31]
	v_mfma_f32_16x16x32_bf16 v[24:27], v[164:167], v[204:207], v[24:27]
	v_mfma_f32_16x16x32_bf16 v[12:15], v[156:159], v[212:215], v[12:15]
	v_mfma_f32_16x16x32_bf16 v[8:11], v[164:167], v[212:215], v[8:11]
	v_mfma_f32_16x16x32_bf16 v[52:55], v[168:171], v[184:187], v[52:55]
	v_mfma_f32_16x16x32_bf16 v[48:51], v[176:179], v[184:187], v[48:51]
	v_mfma_f32_16x16x32_bf16 v[36:39], v[168:171], v[192:195], v[36:39]
	v_mfma_f32_16x16x32_bf16 v[32:35], v[176:179], v[192:195], v[32:35]
	v_mfma_f32_16x16x32_bf16 v[20:23], v[168:171], v[200:203], v[20:23]
	v_mfma_f32_16x16x32_bf16 v[16:19], v[176:179], v[200:203], v[16:19]
	v_mfma_f32_16x16x32_bf16 v[4:7], v[168:171], v[208:211], v[4:7]
	v_mfma_f32_16x16x32_bf16 v[0:3], v[176:179], v[208:211], v[0:3]
	v_mfma_f32_16x16x32_bf16 v[52:55], v[172:175], v[188:191], v[52:55]
	v_mfma_f32_16x16x32_bf16 v[48:51], v[180:183], v[188:191], v[48:51]
	v_mfma_f32_16x16x32_bf16 v[36:39], v[172:175], v[196:199], v[36:39]
	v_mfma_f32_16x16x32_bf16 v[32:35], v[180:183], v[196:199], v[32:35]
	v_mfma_f32_16x16x32_bf16 v[20:23], v[172:175], v[204:207], v[20:23]
	v_mfma_f32_16x16x32_bf16 v[16:19], v[180:183], v[204:207], v[16:19]
	v_mfma_f32_16x16x32_bf16 v[4:7], v[172:175], v[212:215], v[4:7]
	v_mfma_f32_16x16x32_bf16 v[0:3], v[180:183], v[212:215], v[0:3]
	s_barrier
; #define PG8_STAGE(bufoff, gbase, voff) do { _Pragma("unroll") for (int _i = 0; _i < 2; ++_i) \
;         __builtin_amdgcn_global_load_lds((const unsigned*)((const char*)(gbase) + (voff)[_i]), (PG8_LAS unsigned*)(lds + (bufoff) + ldsw + _i * 8192), 16, 0, 0); } while (0)
; #define PG8_LDA(dst, b, h) do { _Pragma("unroll") for (int m = 0; m < 4; ++m) _Pragma("unroll") for (int k = 0; k < 2; ++k) dst[m][k] = *(const PG8_LAS bf16x8*)(lds + PG8_SA(b, h) + aoff + m * 2048 + k * 1024); } while (0)
; #define PG8_LDB(dst, b, h) do { _Pragma("unroll") for (int n = 0; n < 2; ++n) _Pragma("unroll") for (int k = 0; k < 2; ++k) dst[n][k] = *(const PG8_LAS bf16x8*)(lds + PG8_SB(b, h) + boff + n * 2048 + k * 1024); } while (0)
; #define PG8_MMA(ai, bj, At, Bt) do { __builtin_amdgcn_s_setprio(1); _Pragma("unroll") for (int m = 0; m < 4; ++m) _Pragma("unroll") for (int n = 0; n < 2; ++n) _Pragma("unroll") for (int k = 0; k < 2; ++k) \
;         acc[ai][bj][m][n] = __builtin_amdgcn_mfma_f32_16x16x32_bf16(Bt[n][k], At[m][k], acc[ai][bj][m][n], 0, 0, 0); __builtin_amdgcn_s_setprio(0); } while (0)
; #define PG8_WAIT_V(n) asm volatile("s_waitcnt vmcnt(" #n ")" ::: "memory")
; #define PG8_WAIT_L(n) asm volatile("s_waitcnt lgkmcnt(" #n ")" ::: "memory")
; #define PG8_BAR __builtin_amdgcn_s_barrier()
; #define PG8_SCHED __builtin_amdgcn_sched_barrier(0)
; template <class Epi, class Sched, bool ALIGN_EPI = false, bool SP2 = false>
; __device__ __forceinline__ void gemm_phase(PG8_LAS unsigned char* lds, const Gemm g, const Sched& S, const Epi& E) {
;     ...
;             PG8_LDB(B0, 1, 0); PG8_LDB(B1, 1, 1); PG8_SCHED; PG8_LDA(At, 1, 0); PG8_STAGE(PG8_SA(0, 1), a2 + hstep, voffA);
;             PG8_WAIT_V(8); PG8_WAIT_L(0); PG8_BAR; PG8_MMA(0, 0, At, B0); PG8_MMA(0, 1, At, B1); PG8_BAR; PG8_SCHED;
;             PG8_LDA(At, 1, 1); PG8_STAGE(PG8_SB(1, 0), b3, voffB); PG8_STAGE(PG8_SB(1, 1), b3 + hstep, voffB); PG8_STAGE(PG8_SA(1, 0), a3, voffA);
;             PG8_WAIT_V(8); PG8_WAIT_L(0); PG8_BAR; PG8_MMA(1, 0, At, B0); PG8_MMA(1, 1, At, B1); PG8_BAR; PG8_SCHED;
	s_add_i32 s56, 0, 0x18000
	s_add_i32 s57, 0, 0x1c000
	v_add_u32_e32 v164, s56, v152
	v_add_u32_e32 v180, s57, v152
	ds_read_b128 v[146:149], v164
	ds_read_b128 v[156:159], v164 offset:1024
	ds_read_b128 v[160:163], v164 offset:2048
	ds_read_b128 v[164:167], v164 offset:3072
	ds_read_b128 v[168:171], v180
	ds_read_b128 v[172:175], v180 offset:1024
	ds_read_b128 v[176:179], v180 offset:2048
	ds_read_b128 v[180:183], v180 offset:3072
	s_add_u32 s28, s28, 0xb0000
	s_addc_u32 s29, s29, 0
	s_mov_b32 m0, s37
	ds_read_b128 v[184:187], v155 offset:32768
	ds_read_b128 v[188:191], v155 offset:33792
	ds_read_b128 v[192:195], v155 offset:34816
	ds_read_b128 v[196:199], v155 offset:35840
	ds_read_b128 v[200:203], v155 offset:36864
	ds_read_b128 v[204:207], v155 offset:37888
	ds_read_b128 v[208:211], v155 offset:38912
	ds_read_b128 v[212:215], v155 offset:39936
	global_load_lds_dwordx4 v128, s[28:29]
	s_mov_b32 m0, s38
	s_nop 0
	global_load_lds_dwordx4 v132, s[28:29]
	s_waitcnt vmcnt(8)
	s_waitcnt lgkmcnt(0)
	s_barrier
	s_waitcnt lgkmcnt(0)
	v_mfma_f32_16x16x32_bf16 v[124:127], v[146:149], v[184:187], v[124:127]
	v_mfma_f32_16x16x32_bf16 v[120:123], v[160:163], v[184:187], v[120:123]
	v_mfma_f32_16x16x32_bf16 v[108:111], v[146:149], v[192:195], v[108:111]
	v_mfma_f32_16x16x32_bf16 v[104:107], v[160:163], v[192:195], v[104:107]
	v_mfma_f32_16x16x32_bf16 v[92:95], v[146:149], v[200:203], v[92:95]
	v_mfma_f32_16x16x32_bf16 v[88:91], v[160:163], v[200:203], v[88:91]
	v_mfma_f32_16x16x32_bf16 v[76:79], v[146:149], v[208:211], v[76:79]
	v_mfma_f32_16x16x32_bf16 v[72:75], v[160:163], v[208:211], v[72:75]
	v_mfma_f32_16x16x32_bf16 v[124:127], v[156:159], v[188:191], v[124:127]
	v_mfma_f32_16x16x32_bf16 v[120:123], v[164:167], v[188:191], v[120:123]
	v_mfma_f32_16x16x32_bf16 v[108:111], v[156:159], v[196:199], v[108:111]
	v_mfma_f32_16x16x32_bf16 v[104:107], v[164:167], v[196:199], v[104:107]
	v_mfma_f32_16x16x32_bf16 v[92:95], v[156:159], v[204:207], v[92:95]
	v_mfma_f32_16x16x32_bf16 v[88:91], v[164:167], v[204:207], v[88:91]
	v_mfma_f32_16x16x32_bf16 v[76:79], v[156:159], v[212:215], v[76:79]
	v_mfma_f32_16x16x32_bf16 v[72:75], v[164:167], v[212:215], v[72:75]
	v_mfma_f32_16x16x32_bf16 v[116:119], v[168:171], v[184:187], v[116:119]
	v_mfma_f32_16x16x32_bf16 v[112:115], v[176:179], v[184:187], v[112:115]
	v_mfma_f32_16x16x32_bf16 v[100:103], v[168:171], v[192:195], v[100:103]
	v_mfma_f32_16x16x32_bf16 v[96:99], v[176:179], v[192:195], v[96:99]
	v_mfma_f32_16x16x32_bf16 v[84:87], v[168:171], v[200:203], v[84:87]
	v_mfma_f32_16x16x32_bf16 v[80:83], v[176:179], v[200:203], v[80:83]
	v_mfma_f32_16x16x32_bf16 v[68:71], v[168:171], v[208:211], v[68:71]
	v_mfma_f32_16x16x32_bf16 v[64:67], v[176:179], v[208:211], v[64:67]
	v_mfma_f32_16x16x32_bf16 v[116:119], v[172:175], v[188:191], v[116:119]
	v_mfma_f32_16x16x32_bf16 v[112:115], v[180:183], v[188:191], v[112:115]
	v_mfma_f32_16x16x32_bf16 v[100:103], v[172:175], v[196:199], v[100:103]
	v_mfma_f32_16x16x32_bf16 v[96:99], v[180:183], v[196:199], v[96:99]
	v_mfma_f32_16x16x32_bf16 v[84:87], v[172:175], v[204:207], v[84:87]
	v_mfma_f32_16x16x32_bf16 v[80:83], v[180:183], v[204:207], v[80:83]
	v_mfma_f32_16x16x32_bf16 v[68:71], v[172:175], v[212:215], v[68:71]
	v_mfma_f32_16x16x32_bf16 v[64:67], v[180:183], v[212:215], v[64:67]
	s_barrier
	s_add_i32 s28, s56, s31
	s_mov_b32 m0, s28
	ds_read_b128 v[184:187], v155 offset:49152
	ds_read_b128 v[188:191], v155 offset:50176
	ds_read_b128 v[192:195], v155 offset:51200
	ds_read_b128 v[196:199], v155 offset:52224
	ds_read_b128 v[200:203], v155 offset:53248
	ds_read_b128 v[204:207], v155 offset:54272
	ds_read_b128 v[208:211], v155 offset:55296
	ds_read_b128 v[212:215], v155 offset:56320
	s_add_u32 s98, s26, s10
	s_addc_u32 s99, s27, s11
	global_load_lds_dwordx4 v130, s[98:99]
	s_add_i32 m0, s28, 0x2000
	s_add_u32 s26, s26, 0xb0080
	v_lshl_add_u64 v[150:151], v[216:217], 0, s[10:11]
	s_addc_u32 s27, s27, 0
	s_add_i32 s28, s57, s31
	global_load_lds_dwordx4 v[150:151], off
	s_mov_b32 m0, s28
	s_nop 0
	global_load_lds_dwordx4 v130, s[26:27]
	s_add_i32 m0, s28, 0x2000
	s_nop 0
	global_load_lds_dwordx4 v134, s[26:27]
	v_lshl_add_u64 v[150:151], v[218:219], 0, s[10:11]
	s_mov_b32 m0, s40
	s_nop 0
	global_load_lds_dwordx4 v[150:151], off
	v_lshl_add_u64 v[150:151], v[220:221], 0, s[10:11]
	s_mov_b32 m0, s41
	s_nop 0
	global_load_lds_dwordx4 v[150:151], off
	s_waitcnt vmcnt(8)
	s_waitcnt lgkmcnt(0)
	s_barrier
	s_waitcnt lgkmcnt(0)
	v_mfma_f32_16x16x32_bf16 v[60:63], v[146:149], v[184:187], v[60:63]
	v_mfma_f32_16x16x32_bf16 v[56:59], v[160:163], v[184:187], v[56:59]
	v_mfma_f32_16x16x32_bf16 v[44:47], v[146:149], v[192:195], v[44:47]
	v_mfma_f32_16x16x32_bf16 v[40:43], v[160:163], v[192:195], v[40:43]
	v_mfma_f32_16x16x32_bf16 v[28:31], v[146:149], v[200:203], v[28:31]
	v_mfma_f32_16x16x32_bf16 v[24:27], v[160:163], v[200:203], v[24:27]
	v_mfma_f32_16x16x32_bf16 v[12:15], v[146:149], v[208:211], v[12:15]
	v_mfma_f32_16x16x32_bf16 v[8:11], v[160:163], v[208:211], v[8:11]
	v_mfma_f32_16x16x32_bf16 v[60:63], v[156:159], v[188:191], v[60:63]
	v_mfma_f32_16x16x32_bf16 v[56:59], v[164:167], v[188:191], v[56:59]
	v_mfma_f32_16x16x32_bf16 v[44:47], v[156:159], v[196:199], v[44:47]
	v_mfma_f32_16x16x32_bf16 v[40:43], v[164:167], v[196:199], v[40:43]
	v_mfma_f32_16x16x32_bf16 v[28:31], v[156:159], v[204:207], v[28:31]
	v_mfma_f32_16x16x32_bf16 v[24:27], v[164:167], v[204:207], v[24:27]
	v_mfma_f32_16x16x32_bf16 v[12:15], v[156:159], v[212:215], v[12:15]
	v_mfma_f32_16x16x32_bf16 v[8:11], v[164:167], v[212:215], v[8:11]
	v_mfma_f32_16x16x32_bf16 v[52:55], v[168:171], v[184:187], v[52:55]
	v_mfma_f32_16x16x32_bf16 v[48:51], v[176:179], v[184:187], v[48:51]
	v_mfma_f32_16x16x32_bf16 v[36:39], v[168:171], v[192:195], v[36:39]
	v_mfma_f32_16x16x32_bf16 v[32:35], v[176:179], v[192:195], v[32:35]
	v_mfma_f32_16x16x32_bf16 v[20:23], v[168:171], v[200:203], v[20:23]
	v_mfma_f32_16x16x32_bf16 v[16:19], v[176:179], v[200:203], v[16:19]
	v_mfma_f32_16x16x32_bf16 v[4:7], v[168:171], v[208:211], v[4:7]
	v_mfma_f32_16x16x32_bf16 v[0:3], v[176:179], v[208:211], v[0:3]
	v_mfma_f32_16x16x32_bf16 v[52:55], v[172:175], v[188:191], v[52:55]
	v_mfma_f32_16x16x32_bf16 v[48:51], v[180:183], v[188:191], v[48:51]
	v_mfma_f32_16x16x32_bf16 v[36:39], v[172:175], v[196:199], v[36:39]
	v_mfma_f32_16x16x32_bf16 v[32:35], v[180:183], v[196:199], v[32:35]
	v_mfma_f32_16x16x32_bf16 v[20:23], v[172:175], v[204:207], v[20:23]
	v_mfma_f32_16x16x32_bf16 v[16:19], v[180:183], v[204:207], v[16:19]
	v_mfma_f32_16x16x32_bf16 v[4:7], v[172:175], v[212:215], v[4:7]
	v_mfma_f32_16x16x32_bf16 v[0:3], v[180:183], v[212:215], v[0:3]
	s_add_i32 s53, s53, 2
	s_add_u32 s24, s24, 0x100
	s_addc_u32 s25, s25, 0
	s_add_u32 s51, s51, 0x100
	s_addc_u32 s52, s52, 0
	s_cmp_gt_u32 s53, 41
	s_barrier
	s_cbranch_scc0 .LBB0_861
	s_setprio 0
	s_and_b64 vcc, exec, s[12:13]
	s_cbranch_vccz .LBB0_864
	s_barrier
